# bf16 GEMM loops: the MMA wave arrives at its post-MMA barrier one MFMA early (barrier, last MFMA, setprio 0) so the partner wave's wake-up overlaps the last MFMA; pacing-only barrier, LDS protocol unc
# speedup vs baseline: 1.0048x; 1.0048x over previous
.LBB0_170:
	ds_read_b128 v[128:131], v168
	ds_read_b128 v[132:135], v168 offset:1024
	ds_read_b128 v[136:139], v168 offset:2048
	ds_read_b128 v[140:143], v168 offset:3072
	ds_read_b128 v[152:155], v169
	ds_read_b128 v[156:159], v169 offset:1024
	ds_read_b128 v[160:163], v169 offset:2048
	ds_read_b128 v[172:175], v169 offset:3072
	s_add_u32 s2, s52, 0x10000
	s_addc_u32 s3, s53, 0
	s_cmp_eq_u32 s88, 60
	s_cselect_b32 s48, s82, s2
	s_cselect_b32 s49, s39, s3
	s_cselect_b32 s90, s83, s54
	s_cselect_b32 s91, s15, s55
	s_add_u32 s80, s48, 0x8000
	s_addc_u32 s81, s49, 0
	ds_read_b128 v[176:179], v170
	ds_read_b128 v[180:183], v170 offset:1024
	ds_read_b128 v[184:187], v170 offset:2048
	ds_read_b128 v[188:191], v170 offset:3072
	ds_read_b128 v[192:195], v170 offset:4096
	ds_read_b128 v[196:199], v170 offset:5120
	ds_read_b128 v[200:203], v170 offset:6144
	ds_read_b128 v[204:207], v170 offset:7168
	s_add_u32 s92, s52, 0xc000
	s_addc_u32 s93, s53, 0
	s_mov_b32 m0, s72
	s_nop 0
	global_load_lds_dwordx4 v166, s[92:93]
	s_add_u32 s52, s52, 0xe000
	s_addc_u32 s53, s53, 0
	s_mov_b32 m0, s75
	s_nop 0
	global_load_lds_dwordx4 v166, s[52:53]
	s_waitcnt vmcnt(8)
	s_waitcnt lgkmcnt(0)
	s_add_u32 s92, s90, 0x8000
	s_addc_u32 s93, s91, 0
	s_barrier
	s_setprio 1
	s_waitcnt lgkmcnt(7)
	s_waitcnt lgkmcnt(0)
	v_mfma_f32_16x16x32_bf16 v[112:115], v[128:131], v[176:179], v[112:115]
	v_mfma_f32_16x16x32_bf16 v[112:115], v[132:135], v[180:183], v[112:115]
	v_mfma_f32_16x16x32_bf16 v[96:99], v[128:131], v[184:187], v[96:99]
	v_mfma_f32_16x16x32_bf16 v[96:99], v[132:135], v[188:191], v[96:99]
	v_mfma_f32_16x16x32_bf16 v[80:83], v[128:131], v[192:195], v[80:83]
	v_mfma_f32_16x16x32_bf16 v[80:83], v[132:135], v[196:199], v[80:83]
	v_mfma_f32_16x16x32_bf16 v[60:63], v[128:131], v[200:203], v[60:63]
	v_mfma_f32_16x16x32_bf16 v[60:63], v[132:135], v[204:207], v[60:63]
	v_mfma_f32_16x16x32_bf16 v[72:75], v[136:139], v[200:203], v[72:75]
	v_mfma_f32_16x16x32_bf16 v[72:75], v[140:143], v[204:207], v[72:75]
	v_mfma_f32_16x16x32_bf16 v[88:91], v[136:139], v[192:195], v[88:91]
	v_mfma_f32_16x16x32_bf16 v[88:91], v[140:143], v[196:199], v[88:91]
	v_mfma_f32_16x16x32_bf16 v[104:107], v[136:139], v[184:187], v[104:107]
	v_mfma_f32_16x16x32_bf16 v[104:107], v[140:143], v[188:191], v[104:107]
	v_mfma_f32_16x16x32_bf16 v[120:123], v[136:139], v[176:179], v[120:123]
	v_mfma_f32_16x16x32_bf16 v[120:123], v[140:143], v[180:183], v[120:123]
	s_setprio 0
	s_setprio 1
	s_waitcnt lgkmcnt(0)
	v_mfma_f32_16x16x32_bf16 v[116:119], v[152:155], v[176:179], v[116:119]
	v_mfma_f32_16x16x32_bf16 v[116:119], v[156:159], v[180:183], v[116:119]
	v_mfma_f32_16x16x32_bf16 v[100:103], v[152:155], v[184:187], v[100:103]
	v_mfma_f32_16x16x32_bf16 v[100:103], v[156:159], v[188:191], v[100:103]
	v_mfma_f32_16x16x32_bf16 v[84:87], v[152:155], v[192:195], v[84:87]
	v_mfma_f32_16x16x32_bf16 v[84:87], v[156:159], v[196:199], v[84:87]
	v_mfma_f32_16x16x32_bf16 v[68:71], v[152:155], v[200:203], v[68:71]
	v_mfma_f32_16x16x32_bf16 v[68:71], v[156:159], v[204:207], v[68:71]
	v_mfma_f32_16x16x32_bf16 v[76:79], v[160:163], v[200:203], v[76:79]
	v_mfma_f32_16x16x32_bf16 v[76:79], v[172:175], v[204:207], v[76:79]
	v_mfma_f32_16x16x32_bf16 v[92:95], v[160:163], v[192:195], v[92:95]
	v_mfma_f32_16x16x32_bf16 v[92:95], v[172:175], v[196:199], v[92:95]
	v_mfma_f32_16x16x32_bf16 v[108:111], v[160:163], v[184:187], v[108:111]
	v_mfma_f32_16x16x32_bf16 v[108:111], v[172:175], v[188:191], v[108:111]
	v_mfma_f32_16x16x32_bf16 v[124:127], v[160:163], v[176:179], v[124:127]
	s_barrier
	v_mfma_f32_16x16x32_bf16 v[124:127], v[172:175], v[180:183], v[124:127]
	s_setprio 0
	s_add_u32 s52, s90, 0x2000
	ds_read_b128 v[176:179], v170 offset:16384
	ds_read_b128 v[180:183], v170 offset:17408
	ds_read_b128 v[184:187], v170 offset:18432
	ds_read_b128 v[188:191], v170 offset:19456
	ds_read_b128 v[192:195], v170 offset:20480
	ds_read_b128 v[196:199], v170 offset:21504
	ds_read_b128 v[200:203], v170 offset:22528
	ds_read_b128 v[204:207], v170 offset:23552
	s_mov_b32 m0, s45
	s_nop 0
	global_load_lds_dwordx4 v166, s[90:91]
	s_addc_u32 s53, s91, 0
	s_mov_b32 m0, s47
	s_nop 0
	global_load_lds_dwordx4 v166, s[52:53]
	s_add_u32 s52, s90, 0x4000
	s_addc_u32 s53, s91, 0
	s_mov_b32 m0, s58
	s_nop 0
	global_load_lds_dwordx4 v166, s[52:53]
	s_add_u32 s52, s90, 0x6000
	s_addc_u32 s53, s91, 0
	s_mov_b32 m0, s59
	s_nop 0
	global_load_lds_dwordx4 v166, s[52:53]
	s_add_u32 s52, s48, 0x2000
	s_mov_b32 m0, s57
	s_nop 0
	global_load_lds_dwordx4 v166, s[48:49]
	s_addc_u32 s53, s49, 0
	s_mov_b32 m0, s60
	s_nop 0
	global_load_lds_dwordx4 v166, s[52:53]
	s_waitcnt vmcnt(8)
	s_waitcnt lgkmcnt(0)
	s_barrier
	s_setprio 1
	s_waitcnt lgkmcnt(7)
	s_waitcnt lgkmcnt(0)
	v_mfma_f32_16x16x32_bf16 v[48:51], v[128:131], v[176:179], v[48:51]
	v_mfma_f32_16x16x32_bf16 v[48:51], v[132:135], v[180:183], v[48:51]
	v_mfma_f32_16x16x32_bf16 v[32:35], v[128:131], v[184:187], v[32:35]
	v_mfma_f32_16x16x32_bf16 v[32:35], v[132:135], v[188:191], v[32:35]
	v_mfma_f32_16x16x32_bf16 v[16:19], v[128:131], v[192:195], v[16:19]
	v_mfma_f32_16x16x32_bf16 v[16:19], v[132:135], v[196:199], v[16:19]
	v_mfma_f32_16x16x32_bf16 v[0:3], v[128:131], v[200:203], v[0:3]
	v_mfma_f32_16x16x32_bf16 v[0:3], v[132:135], v[204:207], v[0:3]
	v_mfma_f32_16x16x32_bf16 v[8:11], v[136:139], v[200:203], v[8:11]
	v_mfma_f32_16x16x32_bf16 v[8:11], v[140:143], v[204:207], v[8:11]
	v_mfma_f32_16x16x32_bf16 v[24:27], v[136:139], v[192:195], v[24:27]
	v_mfma_f32_16x16x32_bf16 v[24:27], v[140:143], v[196:199], v[24:27]
	v_mfma_f32_16x16x32_bf16 v[40:43], v[136:139], v[184:187], v[40:43]
	v_mfma_f32_16x16x32_bf16 v[40:43], v[140:143], v[188:191], v[40:43]
	v_mfma_f32_16x16x32_bf16 v[56:59], v[136:139], v[176:179], v[56:59]
	v_mfma_f32_16x16x32_bf16 v[56:59], v[140:143], v[180:183], v[56:59]
	s_setprio 0
	s_setprio 1
	s_waitcnt lgkmcnt(0)
	v_mfma_f32_16x16x32_bf16 v[52:55], v[152:155], v[176:179], v[52:55]
	v_mfma_f32_16x16x32_bf16 v[52:55], v[156:159], v[180:183], v[52:55]
	v_mfma_f32_16x16x32_bf16 v[36:39], v[152:155], v[184:187], v[36:39]
	v_mfma_f32_16x16x32_bf16 v[36:39], v[156:159], v[188:191], v[36:39]
	v_mfma_f32_16x16x32_bf16 v[20:23], v[152:155], v[192:195], v[20:23]
	v_mfma_f32_16x16x32_bf16 v[20:23], v[156:159], v[196:199], v[20:23]
	v_mfma_f32_16x16x32_bf16 v[4:7], v[152:155], v[200:203], v[4:7]
	v_mfma_f32_16x16x32_bf16 v[4:7], v[156:159], v[204:207], v[4:7]
	v_mfma_f32_16x16x32_bf16 v[12:15], v[160:163], v[200:203], v[12:15]
	v_mfma_f32_16x16x32_bf16 v[12:15], v[172:175], v[204:207], v[12:15]
	v_mfma_f32_16x16x32_bf16 v[28:31], v[160:163], v[192:195], v[28:31]
	v_mfma_f32_16x16x32_bf16 v[28:31], v[172:175], v[196:199], v[28:31]
	v_mfma_f32_16x16x32_bf16 v[44:47], v[160:163], v[184:187], v[44:47]
	v_mfma_f32_16x16x32_bf16 v[44:47], v[172:175], v[188:191], v[44:47]
	v_mfma_f32_16x16x32_bf16 v[64:67], v[160:163], v[176:179], v[64:67]
	s_barrier
	v_mfma_f32_16x16x32_bf16 v[64:67], v[172:175], v[180:183], v[64:67]
	s_setprio 0
	ds_read_b128 v[128:131], v148
	ds_read_b128 v[132:135], v148 offset:1024
	ds_read_b128 v[136:139], v148 offset:2048
	ds_read_b128 v[140:143], v148 offset:3072
	ds_read_b128 v[152:155], v150
	ds_read_b128 v[156:159], v150 offset:1024
	ds_read_b128 v[160:163], v150 offset:2048
	ds_read_b128 v[172:175], v150 offset:3072
	ds_read_b128 v[176:179], v170 offset:32768
	ds_read_b128 v[180:183], v170 offset:33792
	ds_read_b128 v[184:187], v170 offset:34816
	ds_read_b128 v[188:191], v170 offset:35840
	ds_read_b128 v[192:195], v170 offset:36864
	ds_read_b128 v[196:199], v170 offset:37888
	ds_read_b128 v[200:203], v170 offset:38912
	ds_read_b128 v[204:207], v170 offset:39936
	s_add_u32 s52, s48, 0x4000
	s_addc_u32 s53, s49, 0
	s_mov_b32 m0, s61
	s_nop 0
	global_load_lds_dwordx4 v166, s[52:53]
	s_add_u32 s52, s48, 0x6000
	s_addc_u32 s53, s49, 0
	s_mov_b32 m0, s62
	s_nop 0
	global_load_lds_dwordx4 v166, s[52:53]
	s_waitcnt vmcnt(8)
	s_waitcnt lgkmcnt(0)
	s_barrier
	s_setprio 1
	s_waitcnt lgkmcnt(7)
	s_waitcnt lgkmcnt(0)
	v_mfma_f32_16x16x32_bf16 v[112:115], v[128:131], v[176:179], v[112:115]
	v_mfma_f32_16x16x32_bf16 v[112:115], v[132:135], v[180:183], v[112:115]
	v_mfma_f32_16x16x32_bf16 v[96:99], v[128:131], v[184:187], v[96:99]
	v_mfma_f32_16x16x32_bf16 v[96:99], v[132:135], v[188:191], v[96:99]
	v_mfma_f32_16x16x32_bf16 v[80:83], v[128:131], v[192:195], v[80:83]
	v_mfma_f32_16x16x32_bf16 v[80:83], v[132:135], v[196:199], v[80:83]
	v_mfma_f32_16x16x32_bf16 v[60:63], v[128:131], v[200:203], v[60:63]
	v_mfma_f32_16x16x32_bf16 v[60:63], v[132:135], v[204:207], v[60:63]
	v_mfma_f32_16x16x32_bf16 v[72:75], v[136:139], v[200:203], v[72:75]
	v_mfma_f32_16x16x32_bf16 v[72:75], v[140:143], v[204:207], v[72:75]
	v_mfma_f32_16x16x32_bf16 v[88:91], v[136:139], v[192:195], v[88:91]
	v_mfma_f32_16x16x32_bf16 v[88:91], v[140:143], v[196:199], v[88:91]
	v_mfma_f32_16x16x32_bf16 v[104:107], v[136:139], v[184:187], v[104:107]
	v_mfma_f32_16x16x32_bf16 v[104:107], v[140:143], v[188:191], v[104:107]
	v_mfma_f32_16x16x32_bf16 v[120:123], v[136:139], v[176:179], v[120:123]
	v_mfma_f32_16x16x32_bf16 v[120:123], v[140:143], v[180:183], v[120:123]
	s_setprio 0
	s_setprio 1
	s_waitcnt lgkmcnt(0)
	v_mfma_f32_16x16x32_bf16 v[116:119], v[152:155], v[176:179], v[116:119]
	v_mfma_f32_16x16x32_bf16 v[116:119], v[156:159], v[180:183], v[116:119]
	v_mfma_f32_16x16x32_bf16 v[100:103], v[152:155], v[184:187], v[100:103]
	v_mfma_f32_16x16x32_bf16 v[100:103], v[156:159], v[188:191], v[100:103]
	v_mfma_f32_16x16x32_bf16 v[84:87], v[152:155], v[192:195], v[84:87]
	v_mfma_f32_16x16x32_bf16 v[84:87], v[156:159], v[196:199], v[84:87]
	v_mfma_f32_16x16x32_bf16 v[68:71], v[152:155], v[200:203], v[68:71]
	v_mfma_f32_16x16x32_bf16 v[68:71], v[156:159], v[204:207], v[68:71]
	v_mfma_f32_16x16x32_bf16 v[76:79], v[160:163], v[200:203], v[76:79]
	v_mfma_f32_16x16x32_bf16 v[76:79], v[172:175], v[204:207], v[76:79]
	v_mfma_f32_16x16x32_bf16 v[92:95], v[160:163], v[192:195], v[92:95]
	v_mfma_f32_16x16x32_bf16 v[92:95], v[172:175], v[196:199], v[92:95]
	v_mfma_f32_16x16x32_bf16 v[108:111], v[160:163], v[184:187], v[108:111]
	v_mfma_f32_16x16x32_bf16 v[108:111], v[172:175], v[188:191], v[108:111]
	v_mfma_f32_16x16x32_bf16 v[124:127], v[160:163], v[176:179], v[124:127]
	s_barrier
	v_mfma_f32_16x16x32_bf16 v[124:127], v[172:175], v[180:183], v[124:127]
	s_setprio 0
	s_add_u32 s52, s90, 0xa000
	ds_read_b128 v[176:179], v170 offset:49152
	ds_read_b128 v[180:183], v170 offset:50176
	ds_read_b128 v[184:187], v170 offset:51200
	ds_read_b128 v[188:191], v170 offset:52224
	ds_read_b128 v[192:195], v170 offset:53248
	ds_read_b128 v[196:199], v170 offset:54272
	ds_read_b128 v[200:203], v170 offset:55296
	ds_read_b128 v[204:207], v170 offset:56320
	s_mov_b32 m0, s66
	s_nop 0
	global_load_lds_dwordx4 v166, s[92:93]
	s_addc_u32 s53, s91, 0
	s_mov_b32 m0, s67
	s_nop 0
	global_load_lds_dwordx4 v166, s[52:53]
	s_add_u32 s52, s90, 0xc000
	s_addc_u32 s53, s91, 0
	s_mov_b32 m0, s70
	s_nop 0
	global_load_lds_dwordx4 v166, s[52:53]
	s_add_u32 s52, s90, 0xe000
	s_addc_u32 s53, s91, 0
	s_mov_b32 m0, s71
	s_nop 0
	global_load_lds_dwordx4 v166, s[52:53]
	s_add_u32 s48, s48, 0xa000
	s_mov_b32 m0, s68
	s_nop 0
	global_load_lds_dwordx4 v166, s[80:81]
	s_addc_u32 s49, s49, 0
	s_mov_b32 m0, s69
	s_nop 0
	global_load_lds_dwordx4 v166, s[48:49]
	s_waitcnt vmcnt(8)
	s_waitcnt lgkmcnt(0)
	s_barrier
	s_setprio 1
	s_waitcnt lgkmcnt(7)
	s_waitcnt lgkmcnt(0)
	v_mfma_f32_16x16x32_bf16 v[48:51], v[128:131], v[176:179], v[48:51]
	v_mfma_f32_16x16x32_bf16 v[48:51], v[132:135], v[180:183], v[48:51]
	v_mfma_f32_16x16x32_bf16 v[32:35], v[128:131], v[184:187], v[32:35]
	v_mfma_f32_16x16x32_bf16 v[32:35], v[132:135], v[188:191], v[32:35]
	v_mfma_f32_16x16x32_bf16 v[16:19], v[128:131], v[192:195], v[16:19]
	v_mfma_f32_16x16x32_bf16 v[16:19], v[132:135], v[196:199], v[16:19]
	v_mfma_f32_16x16x32_bf16 v[0:3], v[128:131], v[200:203], v[0:3]
	v_mfma_f32_16x16x32_bf16 v[0:3], v[132:135], v[204:207], v[0:3]
	v_mfma_f32_16x16x32_bf16 v[8:11], v[136:139], v[200:203], v[8:11]
	v_mfma_f32_16x16x32_bf16 v[8:11], v[140:143], v[204:207], v[8:11]
	v_mfma_f32_16x16x32_bf16 v[24:27], v[136:139], v[192:195], v[24:27]
	v_mfma_f32_16x16x32_bf16 v[24:27], v[140:143], v[196:199], v[24:27]
	v_mfma_f32_16x16x32_bf16 v[40:43], v[136:139], v[184:187], v[40:43]
	v_mfma_f32_16x16x32_bf16 v[40:43], v[140:143], v[188:191], v[40:43]
	v_mfma_f32_16x16x32_bf16 v[56:59], v[136:139], v[176:179], v[56:59]
	v_mfma_f32_16x16x32_bf16 v[56:59], v[140:143], v[180:183], v[56:59]
	s_setprio 0
	s_setprio 1
	s_waitcnt lgkmcnt(0)
	v_mfma_f32_16x16x32_bf16 v[52:55], v[152:155], v[176:179], v[52:55]
	v_mfma_f32_16x16x32_bf16 v[52:55], v[156:159], v[180:183], v[52:55]
	v_mfma_f32_16x16x32_bf16 v[36:39], v[152:155], v[184:187], v[36:39]
	v_mfma_f32_16x16x32_bf16 v[36:39], v[156:159], v[188:191], v[36:39]
	v_mfma_f32_16x16x32_bf16 v[20:23], v[152:155], v[192:195], v[20:23]
	v_mfma_f32_16x16x32_bf16 v[20:23], v[156:159], v[196:199], v[20:23]
	v_mfma_f32_16x16x32_bf16 v[4:7], v[152:155], v[200:203], v[4:7]
	v_mfma_f32_16x16x32_bf16 v[4:7], v[156:159], v[204:207], v[4:7]
	v_mfma_f32_16x16x32_bf16 v[12:15], v[160:163], v[200:203], v[12:15]
	v_mfma_f32_16x16x32_bf16 v[12:15], v[172:175], v[204:207], v[12:15]
	v_mfma_f32_16x16x32_bf16 v[28:31], v[160:163], v[192:195], v[28:31]
	v_mfma_f32_16x16x32_bf16 v[28:31], v[172:175], v[196:199], v[28:31]
	v_mfma_f32_16x16x32_bf16 v[44:47], v[160:163], v[184:187], v[44:47]
	v_mfma_f32_16x16x32_bf16 v[44:47], v[172:175], v[188:191], v[44:47]
	v_mfma_f32_16x16x32_bf16 v[64:67], v[160:163], v[176:179], v[64:67]
	s_barrier
	v_mfma_f32_16x16x32_bf16 v[64:67], v[172:175], v[180:183], v[64:67]
	s_setprio 0
	s_nop 7
	s_add_i32 s88, s88, 2
	s_add_u32 s54, s54, 0x10000
	s_addc_u32 s55, s55, 0
	s_cmp_gt_u32 s88, 61
	s_mov_b64 s[52:53], s[2:3]
	s_cbranch_scc0 .LBB0_170
	s_and_b64 vcc, exec, s[12:13]
	s_cbranch_vccz .LBB0_173
	s_barrier

.LBB0_326:
	ds_read_b128 v[60:63], v212
	ds_read_b128 v[68:71], v212 offset:1024
	ds_read_b128 v[88:91], v212 offset:2048
	ds_read_b128 v[92:95], v212 offset:3072
	ds_read_b128 v[112:115], v213
	ds_read_b128 v[116:119], v213 offset:1024
	ds_read_b128 v[138:141], v213 offset:2048
	ds_read_b128 v[152:155], v213 offset:3072
	s_cmpk_eq_i32 s80, 0xa8
	s_cselect_b32 s2, s4, s76
	s_cselect_b32 s3, s5, s77
	s_cselect_b32 s42, s38, s78
	s_cselect_b32 s43, s39, s79
	s_add_u32 s40, s2, 0x8000
	s_addc_u32 s41, s3, 0
	ds_read_b128 v[164:167], v214
	ds_read_b128 v[168:171], v214 offset:1024
	ds_read_b128 v[172:175], v214 offset:2048
	ds_read_b128 v[176:179], v214 offset:3072
	ds_read_b128 v[180:183], v214 offset:4096
	ds_read_b128 v[184:187], v214 offset:5120
	ds_read_b128 v[188:191], v214 offset:6144
	ds_read_b128 v[192:195], v214 offset:7168
	s_add_u32 s44, s76, 0xffffc000
	s_addc_u32 s45, s77, -1
	s_mov_b32 m0, s65
	s_nop 0
	global_load_lds_dwordx4 v210, s[44:45]
	s_add_u32 s44, s76, 0xffffe000
	s_addc_u32 s45, s77, -1
	s_mov_b32 m0, s68
	s_nop 0
	global_load_lds_dwordx4 v210, s[44:45]
	s_waitcnt vmcnt(8)
	s_waitcnt lgkmcnt(0)
	s_add_u32 s44, s42, 0x8000
	s_addc_u32 s45, s43, 0
	s_barrier
	s_setprio 1
	s_waitcnt lgkmcnt(7)
	s_waitcnt lgkmcnt(0)
	v_mfma_f32_16x16x32_bf16 v[160:163], v[60:63], v[164:167], v[160:163]
	v_mfma_f32_16x16x32_bf16 v[160:163], v[68:71], v[168:171], v[160:163]
	v_mfma_f32_16x16x32_bf16 v[132:135], v[60:63], v[172:175], v[132:135]
	v_mfma_f32_16x16x32_bf16 v[132:135], v[68:71], v[176:179], v[132:135]
	v_mfma_f32_16x16x32_bf16 v[108:111], v[60:63], v[180:183], v[108:111]
	v_mfma_f32_16x16x32_bf16 v[108:111], v[68:71], v[184:187], v[108:111]
	v_mfma_f32_16x16x32_bf16 v[84:87], v[60:63], v[188:191], v[84:87]
	v_mfma_f32_16x16x32_bf16 v[84:87], v[68:71], v[192:195], v[84:87]
	v_mfma_f32_16x16x32_bf16 v[80:83], v[88:91], v[188:191], v[80:83]
	v_mfma_f32_16x16x32_bf16 v[80:83], v[92:95], v[192:195], v[80:83]
	v_mfma_f32_16x16x32_bf16 v[104:107], v[88:91], v[180:183], v[104:107]
	v_mfma_f32_16x16x32_bf16 v[104:107], v[92:95], v[184:187], v[104:107]
	v_mfma_f32_16x16x32_bf16 v[128:131], v[88:91], v[172:175], v[128:131]
	v_mfma_f32_16x16x32_bf16 v[128:131], v[92:95], v[176:179], v[128:131]
	v_mfma_f32_16x16x32_bf16 v[156:159], v[88:91], v[164:167], v[156:159]
	v_mfma_f32_16x16x32_bf16 v[156:159], v[92:95], v[168:171], v[156:159]
	s_setprio 0
	s_setprio 1
	v_mfma_f32_16x16x32_bf16 v[148:151], v[112:115], v[164:167], v[148:151]
	v_mfma_f32_16x16x32_bf16 v[142:145], v[138:141], v[164:167], v[144:147]
	v_mfma_f32_16x16x32_bf16 v[124:127], v[112:115], v[172:175], v[124:127]
	v_mfma_f32_16x16x32_bf16 v[120:123], v[138:141], v[172:175], v[120:123]
	v_mfma_f32_16x16x32_bf16 v[100:103], v[112:115], v[180:183], v[100:103]
	v_mfma_f32_16x16x32_bf16 v[96:99], v[138:141], v[180:183], v[96:99]
	v_mfma_f32_16x16x32_bf16 v[76:79], v[112:115], v[188:191], v[76:79]
	v_mfma_f32_16x16x32_bf16 v[72:75], v[138:141], v[188:191], v[72:75]
	v_mfma_f32_16x16x32_bf16 v[148:151], v[116:119], v[168:171], v[148:151]
	v_mfma_f32_16x16x32_bf16 v[142:145], v[152:155], v[168:171], v[142:145]
	v_mfma_f32_16x16x32_bf16 v[124:127], v[116:119], v[176:179], v[124:127]
	v_mfma_f32_16x16x32_bf16 v[120:123], v[152:155], v[176:179], v[120:123]
	v_mfma_f32_16x16x32_bf16 v[100:103], v[116:119], v[184:187], v[100:103]
	v_mfma_f32_16x16x32_bf16 v[96:99], v[152:155], v[184:187], v[96:99]
	v_mfma_f32_16x16x32_bf16 v[76:79], v[116:119], v[192:195], v[76:79]
	v_mfma_f32_16x16x32_bf16 v[72:75], v[152:155], v[192:195], v[72:75]
	s_setprio 0
	s_barrier
	s_add_u32 s82, s42, 0x2000
	ds_read_b128 v[164:167], v214 offset:16384
	ds_read_b128 v[168:171], v214 offset:17408
	ds_read_b128 v[172:175], v214 offset:18432
	ds_read_b128 v[176:179], v214 offset:19456
	ds_read_b128 v[180:183], v214 offset:20480
	ds_read_b128 v[184:187], v214 offset:21504
	ds_read_b128 v[188:191], v214 offset:22528
	ds_read_b128 v[192:195], v214 offset:23552
	s_mov_b32 m0, s47
	s_nop 0
	global_load_lds_dwordx4 v210, s[42:43]
	s_addc_u32 s83, s43, 0
	s_mov_b32 m0, s48
	s_nop 0
	global_load_lds_dwordx4 v210, s[82:83]
	s_add_u32 s82, s42, 0x4000
	s_addc_u32 s83, s43, 0
	s_mov_b32 m0, s49
	s_nop 0
	global_load_lds_dwordx4 v210, s[82:83]
	s_add_u32 s82, s42, 0x6000
	s_addc_u32 s83, s43, 0
	s_mov_b32 m0, s52
	s_nop 0
	global_load_lds_dwordx4 v210, s[82:83]
	s_add_u32 s82, s2, 0x2000
	s_mov_b32 m0, s46
	s_nop 0
	global_load_lds_dwordx4 v210, s[2:3]
	s_addc_u32 s83, s3, 0
	s_mov_b32 m0, s53
	s_nop 0
	global_load_lds_dwordx4 v210, s[82:83]
	s_waitcnt vmcnt(8)
	s_waitcnt lgkmcnt(0)
	s_barrier
	s_setprio 1
	s_waitcnt lgkmcnt(7)
	s_waitcnt lgkmcnt(0)
	v_mfma_f32_16x16x32_bf16 v[64:67], v[60:63], v[164:167], v[64:67]
	v_mfma_f32_16x16x32_bf16 v[64:67], v[68:71], v[168:171], v[64:67]
	v_mfma_f32_16x16x32_bf16 v[44:47], v[60:63], v[172:175], v[44:47]
	v_mfma_f32_16x16x32_bf16 v[44:47], v[68:71], v[176:179], v[44:47]
	v_mfma_f32_16x16x32_bf16 v[28:31], v[60:63], v[180:183], v[28:31]
	v_mfma_f32_16x16x32_bf16 v[28:31], v[68:71], v[184:187], v[28:31]
	v_mfma_f32_16x16x32_bf16 v[12:15], v[60:63], v[188:191], v[12:15]
	v_mfma_f32_16x16x32_bf16 v[12:15], v[68:71], v[192:195], v[12:15]
	v_mfma_f32_16x16x32_bf16 v[8:11], v[88:91], v[188:191], v[8:11]
	v_mfma_f32_16x16x32_bf16 v[8:11], v[92:95], v[192:195], v[8:11]
	v_mfma_f32_16x16x32_bf16 v[24:27], v[88:91], v[180:183], v[24:27]
	v_mfma_f32_16x16x32_bf16 v[24:27], v[92:95], v[184:187], v[24:27]
	v_mfma_f32_16x16x32_bf16 v[40:43], v[88:91], v[172:175], v[40:43]
	v_mfma_f32_16x16x32_bf16 v[40:43], v[92:95], v[176:179], v[40:43]
	v_mfma_f32_16x16x32_bf16 v[56:59], v[88:91], v[164:167], v[56:59]
	v_mfma_f32_16x16x32_bf16 v[56:59], v[92:95], v[168:171], v[56:59]
	s_setprio 0
	s_setprio 1
	s_waitcnt lgkmcnt(0)
	v_mfma_f32_16x16x32_bf16 v[52:55], v[112:115], v[164:167], v[52:55]
	v_mfma_f32_16x16x32_bf16 v[52:55], v[116:119], v[168:171], v[52:55]
	v_mfma_f32_16x16x32_bf16 v[36:39], v[112:115], v[172:175], v[36:39]
	v_mfma_f32_16x16x32_bf16 v[36:39], v[116:119], v[176:179], v[36:39]
	v_mfma_f32_16x16x32_bf16 v[20:23], v[112:115], v[180:183], v[20:23]
	v_mfma_f32_16x16x32_bf16 v[20:23], v[116:119], v[184:187], v[20:23]
	v_mfma_f32_16x16x32_bf16 v[4:7], v[112:115], v[188:191], v[4:7]
	v_mfma_f32_16x16x32_bf16 v[4:7], v[116:119], v[192:195], v[4:7]
	v_mfma_f32_16x16x32_bf16 v[0:3], v[138:141], v[188:191], v[0:3]
	v_mfma_f32_16x16x32_bf16 v[0:3], v[152:155], v[192:195], v[0:3]
	v_mfma_f32_16x16x32_bf16 v[16:19], v[138:141], v[180:183], v[16:19]
	v_mfma_f32_16x16x32_bf16 v[16:19], v[152:155], v[184:187], v[16:19]
	v_mfma_f32_16x16x32_bf16 v[32:35], v[138:141], v[172:175], v[32:35]
	v_mfma_f32_16x16x32_bf16 v[32:35], v[152:155], v[176:179], v[32:35]
	v_mfma_f32_16x16x32_bf16 v[48:51], v[138:141], v[164:167], v[48:51]
	s_barrier
	v_mfma_f32_16x16x32_bf16 v[48:51], v[152:155], v[168:171], v[48:51]
	s_setprio 0
	ds_read_b128 v[60:63], v136
	ds_read_b128 v[68:71], v136 offset:1024
	ds_read_b128 v[88:91], v136 offset:2048
	ds_read_b128 v[92:95], v136 offset:3072
	ds_read_b128 v[112:115], v137
	ds_read_b128 v[116:119], v137 offset:1024
	ds_read_b128 v[138:141], v137 offset:2048
	ds_read_b128 v[152:155], v137 offset:3072
	ds_read_b128 v[164:167], v214 offset:32768
	ds_read_b128 v[168:171], v214 offset:33792
	ds_read_b128 v[172:175], v214 offset:34816
	ds_read_b128 v[176:179], v214 offset:35840
	ds_read_b128 v[180:183], v214 offset:36864
	ds_read_b128 v[184:187], v214 offset:37888
	ds_read_b128 v[188:191], v214 offset:38912
	ds_read_b128 v[192:195], v214 offset:39936
	s_add_u32 s82, s2, 0x4000
	s_addc_u32 s83, s3, 0
	s_mov_b32 m0, s54
	s_nop 0
	global_load_lds_dwordx4 v210, s[82:83]
	s_add_u32 s82, s2, 0x6000
	s_addc_u32 s83, s3, 0
	s_mov_b32 m0, s55
	s_nop 0
	global_load_lds_dwordx4 v210, s[82:83]
	s_waitcnt vmcnt(8)
	s_waitcnt lgkmcnt(0)
	s_barrier
	s_setprio 1
	s_waitcnt lgkmcnt(7)
	s_waitcnt lgkmcnt(0)
	v_mfma_f32_16x16x32_bf16 v[160:163], v[60:63], v[164:167], v[160:163]
	v_mfma_f32_16x16x32_bf16 v[160:163], v[68:71], v[168:171], v[160:163]
	v_mfma_f32_16x16x32_bf16 v[132:135], v[60:63], v[172:175], v[132:135]
	v_mfma_f32_16x16x32_bf16 v[132:135], v[68:71], v[176:179], v[132:135]
	v_mfma_f32_16x16x32_bf16 v[108:111], v[60:63], v[180:183], v[108:111]
	v_mfma_f32_16x16x32_bf16 v[108:111], v[68:71], v[184:187], v[108:111]
	v_mfma_f32_16x16x32_bf16 v[84:87], v[60:63], v[188:191], v[84:87]
	v_mfma_f32_16x16x32_bf16 v[84:87], v[68:71], v[192:195], v[84:87]
	v_mfma_f32_16x16x32_bf16 v[80:83], v[88:91], v[188:191], v[80:83]
	v_mfma_f32_16x16x32_bf16 v[80:83], v[92:95], v[192:195], v[80:83]
	v_mfma_f32_16x16x32_bf16 v[104:107], v[88:91], v[180:183], v[104:107]
	v_mfma_f32_16x16x32_bf16 v[104:107], v[92:95], v[184:187], v[104:107]
	v_mfma_f32_16x16x32_bf16 v[128:131], v[88:91], v[172:175], v[128:131]
	v_mfma_f32_16x16x32_bf16 v[128:131], v[92:95], v[176:179], v[128:131]
	v_mfma_f32_16x16x32_bf16 v[156:159], v[88:91], v[164:167], v[156:159]
	v_mfma_f32_16x16x32_bf16 v[156:159], v[92:95], v[168:171], v[156:159]
	s_setprio 0
	s_setprio 1
	v_mfma_f32_16x16x32_bf16 v[146:149], v[112:115], v[164:167], v[148:151]
	v_mfma_f32_16x16x32_bf16 v[142:145], v[138:141], v[164:167], v[142:145]
	v_mfma_f32_16x16x32_bf16 v[124:127], v[112:115], v[172:175], v[124:127]
	v_mfma_f32_16x16x32_bf16 v[120:123], v[138:141], v[172:175], v[120:123]
	v_mfma_f32_16x16x32_bf16 v[100:103], v[112:115], v[180:183], v[100:103]
	v_mfma_f32_16x16x32_bf16 v[96:99], v[138:141], v[180:183], v[96:99]
	v_mfma_f32_16x16x32_bf16 v[76:79], v[112:115], v[188:191], v[76:79]
	v_mfma_f32_16x16x32_bf16 v[72:75], v[138:141], v[188:191], v[72:75]
	v_mfma_f32_16x16x32_bf16 v[148:151], v[116:119], v[168:171], v[146:149]
	v_mfma_f32_16x16x32_bf16 v[144:147], v[152:155], v[168:171], v[142:145]
	v_mfma_f32_16x16x32_bf16 v[124:127], v[116:119], v[176:179], v[124:127]
	v_mfma_f32_16x16x32_bf16 v[120:123], v[152:155], v[176:179], v[120:123]
	v_mfma_f32_16x16x32_bf16 v[100:103], v[116:119], v[184:187], v[100:103]
	v_mfma_f32_16x16x32_bf16 v[96:99], v[152:155], v[184:187], v[96:99]
	v_mfma_f32_16x16x32_bf16 v[76:79], v[116:119], v[192:195], v[76:79]
	v_mfma_f32_16x16x32_bf16 v[72:75], v[152:155], v[192:195], v[72:75]
	s_setprio 0
	s_barrier
	ds_read_b128 v[164:167], v214 offset:49152
	ds_read_b128 v[168:171], v214 offset:50176
	ds_read_b128 v[172:175], v214 offset:51200
	ds_read_b128 v[176:179], v214 offset:52224
	ds_read_b128 v[180:183], v214 offset:53248
	ds_read_b128 v[184:187], v214 offset:54272
	ds_read_b128 v[188:191], v214 offset:55296
	ds_read_b128 v[192:195], v214 offset:56320
	s_mov_b32 m0, s59
	s_nop 0
	global_load_lds_dwordx4 v210, s[44:45]
	s_add_u32 s44, s42, 0xa000
	s_addc_u32 s45, s43, 0
	s_mov_b32 m0, s60
	s_nop 0
	global_load_lds_dwordx4 v210, s[44:45]
	s_add_u32 s44, s42, 0xc000
	s_addc_u32 s45, s43, 0
	s_mov_b32 m0, s63
	s_nop 0
	global_load_lds_dwordx4 v210, s[44:45]
	s_add_u32 s42, s42, 0xe000
	s_addc_u32 s43, s43, 0
	s_mov_b32 m0, s64
	s_nop 0
	global_load_lds_dwordx4 v210, s[42:43]
	s_add_u32 s2, s2, 0xa000
	s_mov_b32 m0, s61
	s_nop 0
	global_load_lds_dwordx4 v210, s[40:41]
	s_addc_u32 s3, s3, 0
	s_mov_b32 m0, s62
	s_nop 0
	global_load_lds_dwordx4 v210, s[2:3]
	s_waitcnt vmcnt(8)
	s_waitcnt lgkmcnt(0)
	s_barrier
	s_setprio 1
	s_waitcnt lgkmcnt(7)
	s_waitcnt lgkmcnt(0)
	v_mfma_f32_16x16x32_bf16 v[64:67], v[60:63], v[164:167], v[64:67]
	v_mfma_f32_16x16x32_bf16 v[64:67], v[68:71], v[168:171], v[64:67]
	v_mfma_f32_16x16x32_bf16 v[44:47], v[60:63], v[172:175], v[44:47]
	v_mfma_f32_16x16x32_bf16 v[44:47], v[68:71], v[176:179], v[44:47]
	v_mfma_f32_16x16x32_bf16 v[28:31], v[60:63], v[180:183], v[28:31]
	v_mfma_f32_16x16x32_bf16 v[28:31], v[68:71], v[184:187], v[28:31]
	v_mfma_f32_16x16x32_bf16 v[12:15], v[60:63], v[188:191], v[12:15]
	v_mfma_f32_16x16x32_bf16 v[12:15], v[68:71], v[192:195], v[12:15]
	v_mfma_f32_16x16x32_bf16 v[8:11], v[88:91], v[188:191], v[8:11]
	v_mfma_f32_16x16x32_bf16 v[8:11], v[92:95], v[192:195], v[8:11]
	v_mfma_f32_16x16x32_bf16 v[24:27], v[88:91], v[180:183], v[24:27]
	v_mfma_f32_16x16x32_bf16 v[24:27], v[92:95], v[184:187], v[24:27]
	v_mfma_f32_16x16x32_bf16 v[40:43], v[88:91], v[172:175], v[40:43]
	v_mfma_f32_16x16x32_bf16 v[40:43], v[92:95], v[176:179], v[40:43]
	v_mfma_f32_16x16x32_bf16 v[56:59], v[88:91], v[164:167], v[56:59]
	v_mfma_f32_16x16x32_bf16 v[56:59], v[92:95], v[168:171], v[56:59]
	s_setprio 0
	s_setprio 1
	s_waitcnt lgkmcnt(0)
	v_mfma_f32_16x16x32_bf16 v[52:55], v[112:115], v[164:167], v[52:55]
	v_mfma_f32_16x16x32_bf16 v[52:55], v[116:119], v[168:171], v[52:55]
	v_mfma_f32_16x16x32_bf16 v[36:39], v[112:115], v[172:175], v[36:39]
	v_mfma_f32_16x16x32_bf16 v[36:39], v[116:119], v[176:179], v[36:39]
	v_mfma_f32_16x16x32_bf16 v[20:23], v[112:115], v[180:183], v[20:23]
	v_mfma_f32_16x16x32_bf16 v[20:23], v[116:119], v[184:187], v[20:23]
	v_mfma_f32_16x16x32_bf16 v[4:7], v[112:115], v[188:191], v[4:7]
	v_mfma_f32_16x16x32_bf16 v[4:7], v[116:119], v[192:195], v[4:7]
	v_mfma_f32_16x16x32_bf16 v[0:3], v[138:141], v[188:191], v[0:3]
	v_mfma_f32_16x16x32_bf16 v[0:3], v[152:155], v[192:195], v[0:3]
	v_mfma_f32_16x16x32_bf16 v[16:19], v[138:141], v[180:183], v[16:19]
	v_mfma_f32_16x16x32_bf16 v[16:19], v[152:155], v[184:187], v[16:19]
	v_mfma_f32_16x16x32_bf16 v[32:35], v[138:141], v[172:175], v[32:35]
	v_mfma_f32_16x16x32_bf16 v[32:35], v[152:155], v[176:179], v[32:35]
	v_mfma_f32_16x16x32_bf16 v[48:51], v[138:141], v[164:167], v[48:51]
	s_barrier
	v_mfma_f32_16x16x32_bf16 v[48:51], v[152:155], v[168:171], v[48:51]
	s_setprio 0
	s_nop 7
	s_add_i32 s80, s80, 2
	s_add_u32 s76, s76, 0x10000
	s_addc_u32 s77, s77, 0
	s_add_u32 s78, s78, 0x10000
	s_addc_u32 s79, s79, 0
	s_cmpk_gt_u32 s80, 0xa9
	s_cbranch_scc0 .LBB0_326
	s_and_b64 vcc, exec, s[12:13]
	s_cbranch_vccz .LBB0_329
	s_barrier

.LBB0_425:
	ds_read_b128 v[128:131], v162
	ds_read_b128 v[132:135], v162 offset:1024
	ds_read_b128 v[136:139], v162 offset:2048
	ds_read_b128 v[140:143], v162 offset:3072
	ds_read_b128 v[152:155], v163
	ds_read_b128 v[156:159], v163 offset:1024
	ds_read_b128 v[168:171], v163 offset:2048
	ds_read_b128 v[172:175], v163 offset:3072
	s_add_u32 s48, s52, 0x10000
	s_addc_u32 s49, s53, 0
	s_cmp_eq_u32 s79, 60
	s_cselect_b32 s80, s10, s48
	s_cselect_b32 s81, s5, s49
	s_cselect_b32 s96, s47, s77
	s_cselect_b32 s97, s45, s78
	s_add_u32 s2, s80, 0x8000
	s_addc_u32 s3, s81, 0
	ds_read_b128 v[176:179], v164
	ds_read_b128 v[180:183], v164 offset:1024
	ds_read_b128 v[184:187], v164 offset:2048
	ds_read_b128 v[188:191], v164 offset:3072
	ds_read_b128 v[192:195], v164 offset:4096
	ds_read_b128 v[196:199], v164 offset:5120
	ds_read_b128 v[200:203], v164 offset:6144
	ds_read_b128 v[204:207], v164 offset:7168
	s_add_u32 s82, s52, 0xc000
	s_addc_u32 s83, s53, 0
	s_mov_b32 m0, s70
	s_nop 0
	global_load_lds_dwordx4 v160, s[82:83]
	s_add_u32 s52, s52, 0xe000
	s_addc_u32 s53, s53, 0
	s_mov_b32 m0, s71
	s_nop 0
	global_load_lds_dwordx4 v160, s[52:53]
	s_waitcnt vmcnt(8)
	s_waitcnt lgkmcnt(0)
	s_add_u32 s52, s96, 0x8000
	s_addc_u32 s53, s97, 0
	s_barrier
	s_setprio 1
	s_waitcnt lgkmcnt(7)
	s_waitcnt lgkmcnt(0)
	v_mfma_f32_16x16x32_bf16 v[124:127], v[128:131], v[176:179], v[124:127]
	v_mfma_f32_16x16x32_bf16 v[124:127], v[132:135], v[180:183], v[124:127]
	v_mfma_f32_16x16x32_bf16 v[108:111], v[128:131], v[184:187], v[108:111]
	v_mfma_f32_16x16x32_bf16 v[108:111], v[132:135], v[188:191], v[108:111]
	v_mfma_f32_16x16x32_bf16 v[92:95], v[128:131], v[192:195], v[92:95]
	v_mfma_f32_16x16x32_bf16 v[92:95], v[132:135], v[196:199], v[92:95]
	v_mfma_f32_16x16x32_bf16 v[76:79], v[128:131], v[200:203], v[76:79]
	v_mfma_f32_16x16x32_bf16 v[76:79], v[132:135], v[204:207], v[76:79]
	v_mfma_f32_16x16x32_bf16 v[72:75], v[136:139], v[200:203], v[72:75]
	v_mfma_f32_16x16x32_bf16 v[72:75], v[140:143], v[204:207], v[72:75]
	v_mfma_f32_16x16x32_bf16 v[88:91], v[136:139], v[192:195], v[88:91]
	v_mfma_f32_16x16x32_bf16 v[88:91], v[140:143], v[196:199], v[88:91]
	v_mfma_f32_16x16x32_bf16 v[104:107], v[136:139], v[184:187], v[104:107]
	v_mfma_f32_16x16x32_bf16 v[104:107], v[140:143], v[188:191], v[104:107]
	v_mfma_f32_16x16x32_bf16 v[120:123], v[136:139], v[176:179], v[120:123]
	v_mfma_f32_16x16x32_bf16 v[120:123], v[140:143], v[180:183], v[120:123]
	s_setprio 0
	s_setprio 1
	s_waitcnt lgkmcnt(0)
	v_mfma_f32_16x16x32_bf16 v[116:119], v[152:155], v[176:179], v[116:119]
	v_mfma_f32_16x16x32_bf16 v[116:119], v[156:159], v[180:183], v[116:119]
	v_mfma_f32_16x16x32_bf16 v[100:103], v[152:155], v[184:187], v[100:103]
	v_mfma_f32_16x16x32_bf16 v[100:103], v[156:159], v[188:191], v[100:103]
	v_mfma_f32_16x16x32_bf16 v[84:87], v[152:155], v[192:195], v[84:87]
	v_mfma_f32_16x16x32_bf16 v[84:87], v[156:159], v[196:199], v[84:87]
	v_mfma_f32_16x16x32_bf16 v[68:71], v[152:155], v[200:203], v[68:71]
	v_mfma_f32_16x16x32_bf16 v[68:71], v[156:159], v[204:207], v[68:71]
	v_mfma_f32_16x16x32_bf16 v[64:67], v[168:171], v[200:203], v[64:67]
	v_mfma_f32_16x16x32_bf16 v[64:67], v[172:175], v[204:207], v[64:67]
	v_mfma_f32_16x16x32_bf16 v[80:83], v[168:171], v[192:195], v[80:83]
	v_mfma_f32_16x16x32_bf16 v[80:83], v[172:175], v[196:199], v[80:83]
	v_mfma_f32_16x16x32_bf16 v[96:99], v[168:171], v[184:187], v[96:99]
	v_mfma_f32_16x16x32_bf16 v[96:99], v[172:175], v[188:191], v[96:99]
	v_mfma_f32_16x16x32_bf16 v[112:115], v[168:171], v[176:179], v[112:115]
	s_barrier
	v_mfma_f32_16x16x32_bf16 v[112:115], v[172:175], v[180:183], v[112:115]
	s_setprio 0
	s_add_u32 s82, s96, 0x2000
	ds_read_b128 v[176:179], v164 offset:16384
	ds_read_b128 v[180:183], v164 offset:17408
	ds_read_b128 v[184:187], v164 offset:18432
	ds_read_b128 v[188:191], v164 offset:19456
	ds_read_b128 v[192:195], v164 offset:20480
	ds_read_b128 v[196:199], v164 offset:21504
	ds_read_b128 v[200:203], v164 offset:22528
	ds_read_b128 v[204:207], v164 offset:23552
	s_mov_b32 m0, s55
	s_nop 0
	global_load_lds_dwordx4 v160, s[96:97]
	s_addc_u32 s83, s97, 0
	s_mov_b32 m0, s56
	s_nop 0
	global_load_lds_dwordx4 v160, s[82:83]
	s_add_u32 s82, s96, 0x4000
	s_addc_u32 s83, s97, 0
	s_mov_b32 m0, s57
	s_nop 0
	global_load_lds_dwordx4 v160, s[82:83]
	s_add_u32 s82, s96, 0x6000
	s_addc_u32 s83, s97, 0
	s_mov_b32 m0, s58
	s_nop 0
	global_load_lds_dwordx4 v160, s[82:83]
	s_add_u32 s82, s80, 0x2000
	s_mov_b32 m0, s54
	s_nop 0
	global_load_lds_dwordx4 v160, s[80:81]
	s_addc_u32 s83, s81, 0
	s_mov_b32 m0, s59
	s_nop 0
	global_load_lds_dwordx4 v160, s[82:83]
	s_waitcnt vmcnt(8)
	s_waitcnt lgkmcnt(0)
	s_barrier
	s_setprio 1
	s_waitcnt lgkmcnt(7)
	s_waitcnt lgkmcnt(0)
	v_mfma_f32_16x16x32_bf16 v[60:63], v[128:131], v[176:179], v[60:63]
	v_mfma_f32_16x16x32_bf16 v[60:63], v[132:135], v[180:183], v[60:63]
	v_mfma_f32_16x16x32_bf16 v[44:47], v[128:131], v[184:187], v[44:47]
	v_mfma_f32_16x16x32_bf16 v[44:47], v[132:135], v[188:191], v[44:47]
	v_mfma_f32_16x16x32_bf16 v[28:31], v[128:131], v[192:195], v[28:31]
	v_mfma_f32_16x16x32_bf16 v[28:31], v[132:135], v[196:199], v[28:31]
	v_mfma_f32_16x16x32_bf16 v[12:15], v[128:131], v[200:203], v[12:15]
	v_mfma_f32_16x16x32_bf16 v[12:15], v[132:135], v[204:207], v[12:15]
	v_mfma_f32_16x16x32_bf16 v[8:11], v[136:139], v[200:203], v[8:11]
	v_mfma_f32_16x16x32_bf16 v[8:11], v[140:143], v[204:207], v[8:11]
	v_mfma_f32_16x16x32_bf16 v[24:27], v[136:139], v[192:195], v[24:27]
	v_mfma_f32_16x16x32_bf16 v[24:27], v[140:143], v[196:199], v[24:27]
	v_mfma_f32_16x16x32_bf16 v[40:43], v[136:139], v[184:187], v[40:43]
	v_mfma_f32_16x16x32_bf16 v[40:43], v[140:143], v[188:191], v[40:43]
	v_mfma_f32_16x16x32_bf16 v[56:59], v[136:139], v[176:179], v[56:59]
	v_mfma_f32_16x16x32_bf16 v[56:59], v[140:143], v[180:183], v[56:59]
	s_setprio 0
	s_setprio 1
	s_waitcnt lgkmcnt(0)
	v_mfma_f32_16x16x32_bf16 v[52:55], v[152:155], v[176:179], v[52:55]
	v_mfma_f32_16x16x32_bf16 v[52:55], v[156:159], v[180:183], v[52:55]
	v_mfma_f32_16x16x32_bf16 v[36:39], v[152:155], v[184:187], v[36:39]
	v_mfma_f32_16x16x32_bf16 v[36:39], v[156:159], v[188:191], v[36:39]
	v_mfma_f32_16x16x32_bf16 v[20:23], v[152:155], v[192:195], v[20:23]
	v_mfma_f32_16x16x32_bf16 v[20:23], v[156:159], v[196:199], v[20:23]
	v_mfma_f32_16x16x32_bf16 v[4:7], v[152:155], v[200:203], v[4:7]
	v_mfma_f32_16x16x32_bf16 v[4:7], v[156:159], v[204:207], v[4:7]
	v_mfma_f32_16x16x32_bf16 v[0:3], v[168:171], v[200:203], v[0:3]
	v_mfma_f32_16x16x32_bf16 v[0:3], v[172:175], v[204:207], v[0:3]
	v_mfma_f32_16x16x32_bf16 v[16:19], v[168:171], v[192:195], v[16:19]
	v_mfma_f32_16x16x32_bf16 v[16:19], v[172:175], v[196:199], v[16:19]
	v_mfma_f32_16x16x32_bf16 v[32:35], v[168:171], v[184:187], v[32:35]
	v_mfma_f32_16x16x32_bf16 v[32:35], v[172:175], v[188:191], v[32:35]
	v_mfma_f32_16x16x32_bf16 v[48:51], v[168:171], v[176:179], v[48:51]
	s_barrier
	v_mfma_f32_16x16x32_bf16 v[48:51], v[172:175], v[180:183], v[48:51]
	s_setprio 0
	ds_read_b128 v[128:131], v148
	ds_read_b128 v[132:135], v148 offset:1024
	ds_read_b128 v[136:139], v148 offset:2048
	ds_read_b128 v[140:143], v148 offset:3072
	ds_read_b128 v[152:155], v150
	ds_read_b128 v[156:159], v150 offset:1024
	ds_read_b128 v[168:171], v150 offset:2048
	ds_read_b128 v[172:175], v150 offset:3072
	ds_read_b128 v[176:179], v164 offset:32768
	ds_read_b128 v[180:183], v164 offset:33792
	ds_read_b128 v[184:187], v164 offset:34816
	ds_read_b128 v[188:191], v164 offset:35840
	ds_read_b128 v[192:195], v164 offset:36864
	ds_read_b128 v[196:199], v164 offset:37888
	ds_read_b128 v[200:203], v164 offset:38912
	ds_read_b128 v[204:207], v164 offset:39936
	s_add_u32 s82, s80, 0x4000
	s_addc_u32 s83, s81, 0
	s_mov_b32 m0, s60
	s_nop 0
	global_load_lds_dwordx4 v160, s[82:83]
	s_add_u32 s82, s80, 0x6000
	s_addc_u32 s83, s81, 0
	s_mov_b32 m0, s61
	s_nop 0
	global_load_lds_dwordx4 v160, s[82:83]
	s_waitcnt vmcnt(8)
	s_waitcnt lgkmcnt(0)
	s_barrier
	s_setprio 1
	s_waitcnt lgkmcnt(7)
	s_waitcnt lgkmcnt(0)
	v_mfma_f32_16x16x32_bf16 v[124:127], v[128:131], v[176:179], v[124:127]
	v_mfma_f32_16x16x32_bf16 v[124:127], v[132:135], v[180:183], v[124:127]
	v_mfma_f32_16x16x32_bf16 v[108:111], v[128:131], v[184:187], v[108:111]
	v_mfma_f32_16x16x32_bf16 v[108:111], v[132:135], v[188:191], v[108:111]
	v_mfma_f32_16x16x32_bf16 v[92:95], v[128:131], v[192:195], v[92:95]
	v_mfma_f32_16x16x32_bf16 v[92:95], v[132:135], v[196:199], v[92:95]
	v_mfma_f32_16x16x32_bf16 v[76:79], v[128:131], v[200:203], v[76:79]
	v_mfma_f32_16x16x32_bf16 v[76:79], v[132:135], v[204:207], v[76:79]
	v_mfma_f32_16x16x32_bf16 v[72:75], v[136:139], v[200:203], v[72:75]
	v_mfma_f32_16x16x32_bf16 v[72:75], v[140:143], v[204:207], v[72:75]
	v_mfma_f32_16x16x32_bf16 v[88:91], v[136:139], v[192:195], v[88:91]
	v_mfma_f32_16x16x32_bf16 v[88:91], v[140:143], v[196:199], v[88:91]
	v_mfma_f32_16x16x32_bf16 v[104:107], v[136:139], v[184:187], v[104:107]
	v_mfma_f32_16x16x32_bf16 v[104:107], v[140:143], v[188:191], v[104:107]
	v_mfma_f32_16x16x32_bf16 v[120:123], v[136:139], v[176:179], v[120:123]
	v_mfma_f32_16x16x32_bf16 v[120:123], v[140:143], v[180:183], v[120:123]
	s_setprio 0
	s_setprio 1
	s_waitcnt lgkmcnt(0)
	v_mfma_f32_16x16x32_bf16 v[116:119], v[152:155], v[176:179], v[116:119]
	v_mfma_f32_16x16x32_bf16 v[116:119], v[156:159], v[180:183], v[116:119]
	v_mfma_f32_16x16x32_bf16 v[100:103], v[152:155], v[184:187], v[100:103]
	v_mfma_f32_16x16x32_bf16 v[100:103], v[156:159], v[188:191], v[100:103]
	v_mfma_f32_16x16x32_bf16 v[84:87], v[152:155], v[192:195], v[84:87]
	v_mfma_f32_16x16x32_bf16 v[84:87], v[156:159], v[196:199], v[84:87]
	v_mfma_f32_16x16x32_bf16 v[68:71], v[152:155], v[200:203], v[68:71]
	v_mfma_f32_16x16x32_bf16 v[68:71], v[156:159], v[204:207], v[68:71]
	v_mfma_f32_16x16x32_bf16 v[64:67], v[168:171], v[200:203], v[64:67]
	v_mfma_f32_16x16x32_bf16 v[64:67], v[172:175], v[204:207], v[64:67]
	v_mfma_f32_16x16x32_bf16 v[80:83], v[168:171], v[192:195], v[80:83]
	v_mfma_f32_16x16x32_bf16 v[80:83], v[172:175], v[196:199], v[80:83]
	v_mfma_f32_16x16x32_bf16 v[96:99], v[168:171], v[184:187], v[96:99]
	v_mfma_f32_16x16x32_bf16 v[96:99], v[172:175], v[188:191], v[96:99]
	v_mfma_f32_16x16x32_bf16 v[112:115], v[168:171], v[176:179], v[112:115]
	s_barrier
	v_mfma_f32_16x16x32_bf16 v[112:115], v[172:175], v[180:183], v[112:115]
	s_setprio 0
	ds_read_b128 v[176:179], v164 offset:49152
	ds_read_b128 v[180:183], v164 offset:50176
	ds_read_b128 v[184:187], v164 offset:51200
	ds_read_b128 v[188:191], v164 offset:52224
	ds_read_b128 v[192:195], v164 offset:53248
	ds_read_b128 v[196:199], v164 offset:54272
	ds_read_b128 v[200:203], v164 offset:55296
	ds_read_b128 v[204:207], v164 offset:56320
	s_mov_b32 m0, s64
	s_nop 0
	global_load_lds_dwordx4 v160, s[52:53]
	s_add_u32 s52, s96, 0xa000
	s_addc_u32 s53, s97, 0
	s_mov_b32 m0, s65
	s_nop 0
	global_load_lds_dwordx4 v160, s[52:53]
	s_add_u32 s52, s96, 0xc000
	s_addc_u32 s53, s97, 0
	s_mov_b32 m0, s68
	s_nop 0
	global_load_lds_dwordx4 v160, s[52:53]
	s_add_u32 s52, s96, 0xe000
	s_addc_u32 s53, s97, 0
	s_mov_b32 m0, s69
	s_nop 0
	global_load_lds_dwordx4 v160, s[52:53]
	s_nop 0
	s_mov_b32 m0, s66
	s_nop 0
	global_load_lds_dwordx4 v160, s[2:3]
	s_add_u32 s2, s80, 0xa000
	s_addc_u32 s3, s81, 0
	s_mov_b32 m0, s67
	s_nop 0
	global_load_lds_dwordx4 v160, s[2:3]
	s_waitcnt vmcnt(8)
	s_waitcnt lgkmcnt(0)
	s_barrier
	s_setprio 1
	s_waitcnt lgkmcnt(7)
	s_waitcnt lgkmcnt(0)
	v_mfma_f32_16x16x32_bf16 v[60:63], v[128:131], v[176:179], v[60:63]
	v_mfma_f32_16x16x32_bf16 v[60:63], v[132:135], v[180:183], v[60:63]
	v_mfma_f32_16x16x32_bf16 v[44:47], v[128:131], v[184:187], v[44:47]
	v_mfma_f32_16x16x32_bf16 v[44:47], v[132:135], v[188:191], v[44:47]
	v_mfma_f32_16x16x32_bf16 v[28:31], v[128:131], v[192:195], v[28:31]
	v_mfma_f32_16x16x32_bf16 v[28:31], v[132:135], v[196:199], v[28:31]
	v_mfma_f32_16x16x32_bf16 v[12:15], v[128:131], v[200:203], v[12:15]
	v_mfma_f32_16x16x32_bf16 v[12:15], v[132:135], v[204:207], v[12:15]
	v_mfma_f32_16x16x32_bf16 v[8:11], v[136:139], v[200:203], v[8:11]
	v_mfma_f32_16x16x32_bf16 v[8:11], v[140:143], v[204:207], v[8:11]
	v_mfma_f32_16x16x32_bf16 v[24:27], v[136:139], v[192:195], v[24:27]
	v_mfma_f32_16x16x32_bf16 v[24:27], v[140:143], v[196:199], v[24:27]
	v_mfma_f32_16x16x32_bf16 v[40:43], v[136:139], v[184:187], v[40:43]
	v_mfma_f32_16x16x32_bf16 v[40:43], v[140:143], v[188:191], v[40:43]
	v_mfma_f32_16x16x32_bf16 v[56:59], v[136:139], v[176:179], v[56:59]
	v_mfma_f32_16x16x32_bf16 v[56:59], v[140:143], v[180:183], v[56:59]
	s_setprio 0
	s_setprio 1
	s_waitcnt lgkmcnt(0)
	v_mfma_f32_16x16x32_bf16 v[52:55], v[152:155], v[176:179], v[52:55]
	v_mfma_f32_16x16x32_bf16 v[52:55], v[156:159], v[180:183], v[52:55]
	v_mfma_f32_16x16x32_bf16 v[36:39], v[152:155], v[184:187], v[36:39]
	v_mfma_f32_16x16x32_bf16 v[36:39], v[156:159], v[188:191], v[36:39]
	v_mfma_f32_16x16x32_bf16 v[20:23], v[152:155], v[192:195], v[20:23]
	v_mfma_f32_16x16x32_bf16 v[20:23], v[156:159], v[196:199], v[20:23]
	v_mfma_f32_16x16x32_bf16 v[4:7], v[152:155], v[200:203], v[4:7]
	v_mfma_f32_16x16x32_bf16 v[4:7], v[156:159], v[204:207], v[4:7]
	v_mfma_f32_16x16x32_bf16 v[0:3], v[168:171], v[200:203], v[0:3]
	v_mfma_f32_16x16x32_bf16 v[0:3], v[172:175], v[204:207], v[0:3]
	v_mfma_f32_16x16x32_bf16 v[16:19], v[168:171], v[192:195], v[16:19]
	v_mfma_f32_16x16x32_bf16 v[16:19], v[172:175], v[196:199], v[16:19]
	v_mfma_f32_16x16x32_bf16 v[32:35], v[168:171], v[184:187], v[32:35]
	v_mfma_f32_16x16x32_bf16 v[32:35], v[172:175], v[188:191], v[32:35]
	v_mfma_f32_16x16x32_bf16 v[48:51], v[168:171], v[176:179], v[48:51]
	s_barrier
	v_mfma_f32_16x16x32_bf16 v[48:51], v[172:175], v[180:183], v[48:51]
	s_setprio 0
	s_nop 7
	s_add_i32 s79, s79, 2
	s_add_u32 s77, s77, 0x10000
	s_addc_u32 s78, s78, 0
	s_cmp_gt_u32 s79, 61
	s_mov_b64 s[52:53], s[48:49]
	s_cbranch_scc0 .LBB0_425
	s_and_b64 vcc, exec, s[14:15]
	s_cbranch_vccz .LBB0_428
	s_barrier

.LBB0_1406:
	ds_read_b128 v[72:75], v212
	ds_read_b128 v[84:87], v212 offset:1024
	ds_read_b128 v[96:99], v212 offset:2048
	ds_read_b128 v[108:111], v212 offset:3072
	ds_read_b128 v[112:115], v213
	ds_read_b128 v[136:139], v213 offset:1024
	ds_read_b128 v[148:151], v213 offset:2048
	ds_read_b128 v[160:163], v213 offset:3072
	s_cmp_eq_u32 s90, 60
	s_cselect_b32 s2, s82, s54
	s_cselect_b32 s3, s41, s55
	s_cselect_b32 s58, s83, s88
	s_cselect_b32 s59, s39, s89
	s_add_u32 s56, s2, 0x8000
	s_addc_u32 s57, s3, 0
	ds_read_b128 v[164:167], v214
	ds_read_b128 v[168:171], v214 offset:1024
	ds_read_b128 v[172:175], v214 offset:2048
	ds_read_b128 v[176:179], v214 offset:3072
	ds_read_b128 v[180:183], v214 offset:4096
	ds_read_b128 v[184:187], v214 offset:5120
	ds_read_b128 v[188:191], v214 offset:6144
	ds_read_b128 v[192:195], v214 offset:7168
	s_add_u32 s52, s54, 0xffffc000
	s_addc_u32 s53, s55, -1
	s_mov_b32 m0, s75
	s_nop 0
	global_load_lds_dwordx4 v210, s[52:53]
	s_add_u32 s52, s54, 0xffffe000
	s_addc_u32 s53, s55, -1
	s_mov_b32 m0, s78
	s_nop 0
	global_load_lds_dwordx4 v210, s[52:53]
	s_waitcnt vmcnt(8)
	s_waitcnt lgkmcnt(0)
	s_add_u32 s52, s58, 0x8000
	s_addc_u32 s53, s59, 0
	s_barrier
	s_setprio 1
	s_waitcnt lgkmcnt(7)
	v_mfma_f32_16x16x32_bf16 v[156:159], v[72:75], v[164:167], v[156:159]
	v_mfma_f32_16x16x32_bf16 v[152:155], v[96:99], v[164:167], v[152:155]
	s_waitcnt lgkmcnt(5)
	v_mfma_f32_16x16x32_bf16 v[132:135], v[72:75], v[172:175], v[132:135]
	v_mfma_f32_16x16x32_bf16 v[126:129], v[96:99], v[172:175], v[128:131]
	s_waitcnt lgkmcnt(3)
	v_mfma_f32_16x16x32_bf16 v[104:107], v[72:75], v[180:183], v[104:107]
	v_mfma_f32_16x16x32_bf16 v[100:103], v[96:99], v[180:183], v[100:103]
	s_waitcnt lgkmcnt(1)
	v_mfma_f32_16x16x32_bf16 v[80:83], v[72:75], v[188:191], v[80:83]
	v_mfma_f32_16x16x32_bf16 v[76:79], v[96:99], v[188:191], v[76:79]
	v_mfma_f32_16x16x32_bf16 v[156:159], v[84:87], v[168:171], v[156:159]
	v_mfma_f32_16x16x32_bf16 v[152:155], v[108:111], v[168:171], v[152:155]
	v_mfma_f32_16x16x32_bf16 v[132:135], v[84:87], v[176:179], v[132:135]
	v_mfma_f32_16x16x32_bf16 v[126:129], v[108:111], v[176:179], v[126:129]
	v_mfma_f32_16x16x32_bf16 v[104:107], v[84:87], v[184:187], v[104:107]
	v_mfma_f32_16x16x32_bf16 v[100:103], v[108:111], v[184:187], v[100:103]
	s_waitcnt lgkmcnt(0)
	v_mfma_f32_16x16x32_bf16 v[80:83], v[84:87], v[192:195], v[80:83]
	v_mfma_f32_16x16x32_bf16 v[76:79], v[108:111], v[192:195], v[76:79]
	s_setprio 0
	s_setprio 1
	s_waitcnt lgkmcnt(0)
	v_mfma_f32_16x16x32_bf16 v[144:147], v[112:115], v[164:167], v[144:147]
	v_mfma_f32_16x16x32_bf16 v[144:147], v[136:139], v[168:171], v[144:147]
	v_mfma_f32_16x16x32_bf16 v[120:123], v[112:115], v[172:175], v[120:123]
	v_mfma_f32_16x16x32_bf16 v[120:123], v[136:139], v[176:179], v[120:123]
	v_mfma_f32_16x16x32_bf16 v[92:95], v[112:115], v[180:183], v[92:95]
	v_mfma_f32_16x16x32_bf16 v[92:95], v[136:139], v[184:187], v[92:95]
	v_mfma_f32_16x16x32_bf16 v[68:71], v[112:115], v[188:191], v[68:71]
	v_mfma_f32_16x16x32_bf16 v[68:71], v[136:139], v[192:195], v[68:71]
	v_mfma_f32_16x16x32_bf16 v[64:67], v[148:151], v[188:191], v[64:67]
	v_mfma_f32_16x16x32_bf16 v[64:67], v[160:163], v[192:195], v[64:67]
	v_mfma_f32_16x16x32_bf16 v[88:91], v[148:151], v[180:183], v[88:91]
	v_mfma_f32_16x16x32_bf16 v[88:91], v[160:163], v[184:187], v[88:91]
	v_mfma_f32_16x16x32_bf16 v[116:119], v[148:151], v[172:175], v[116:119]
	v_mfma_f32_16x16x32_bf16 v[116:119], v[160:163], v[176:179], v[116:119]
	v_mfma_f32_16x16x32_bf16 v[140:143], v[148:151], v[164:167], v[140:143]
	s_barrier
	v_mfma_f32_16x16x32_bf16 v[140:143], v[160:163], v[168:171], v[140:143]
	s_setprio 0
	s_add_u32 s92, s58, 0x2000
	ds_read_b128 v[164:167], v214 offset:16384
	ds_read_b128 v[168:171], v214 offset:17408
	ds_read_b128 v[172:175], v214 offset:18432
	ds_read_b128 v[176:179], v214 offset:19456
	ds_read_b128 v[180:183], v214 offset:20480
	ds_read_b128 v[184:187], v214 offset:21504
	ds_read_b128 v[188:191], v214 offset:22528
	ds_read_b128 v[192:195], v214 offset:23552
	s_mov_b32 m0, s47
	s_nop 0
	global_load_lds_dwordx4 v210, s[58:59]
	s_addc_u32 s93, s59, 0
	s_mov_b32 m0, s49
	s_nop 0
	global_load_lds_dwordx4 v210, s[92:93]
	s_add_u32 s92, s58, 0x4000
	s_addc_u32 s93, s59, 0
	s_mov_b32 m0, s61
	s_nop 0
	global_load_lds_dwordx4 v210, s[92:93]
	s_add_u32 s92, s58, 0x6000
	s_addc_u32 s93, s59, 0
	s_mov_b32 m0, s62
	s_nop 0
	global_load_lds_dwordx4 v210, s[92:93]
	s_add_u32 s92, s2, 0x2000
	s_mov_b32 m0, s60
	s_nop 0
	global_load_lds_dwordx4 v210, s[2:3]
	s_addc_u32 s93, s3, 0
	s_mov_b32 m0, s63
	s_nop 0
	global_load_lds_dwordx4 v210, s[92:93]
	s_waitcnt vmcnt(8)
	s_waitcnt lgkmcnt(0)
	s_barrier
	s_setprio 1
	s_waitcnt lgkmcnt(7)
	s_waitcnt lgkmcnt(0)
	v_mfma_f32_16x16x32_bf16 v[60:63], v[72:75], v[164:167], v[60:63]
	v_mfma_f32_16x16x32_bf16 v[60:63], v[84:87], v[168:171], v[60:63]
	v_mfma_f32_16x16x32_bf16 v[44:47], v[72:75], v[172:175], v[44:47]
	v_mfma_f32_16x16x32_bf16 v[44:47], v[84:87], v[176:179], v[44:47]
	v_mfma_f32_16x16x32_bf16 v[28:31], v[72:75], v[180:183], v[28:31]
	v_mfma_f32_16x16x32_bf16 v[28:31], v[84:87], v[184:187], v[28:31]
	v_mfma_f32_16x16x32_bf16 v[12:15], v[72:75], v[188:191], v[12:15]
	v_mfma_f32_16x16x32_bf16 v[12:15], v[84:87], v[192:195], v[12:15]
	v_mfma_f32_16x16x32_bf16 v[8:11], v[96:99], v[188:191], v[8:11]
	v_mfma_f32_16x16x32_bf16 v[8:11], v[108:111], v[192:195], v[8:11]
	v_mfma_f32_16x16x32_bf16 v[24:27], v[96:99], v[180:183], v[24:27]
	v_mfma_f32_16x16x32_bf16 v[24:27], v[108:111], v[184:187], v[24:27]
	v_mfma_f32_16x16x32_bf16 v[40:43], v[96:99], v[172:175], v[40:43]
	v_mfma_f32_16x16x32_bf16 v[40:43], v[108:111], v[176:179], v[40:43]
	v_mfma_f32_16x16x32_bf16 v[56:59], v[96:99], v[164:167], v[56:59]
	v_mfma_f32_16x16x32_bf16 v[56:59], v[108:111], v[168:171], v[56:59]
	s_setprio 0
	s_setprio 1
	s_waitcnt lgkmcnt(0)
	v_mfma_f32_16x16x32_bf16 v[52:55], v[112:115], v[164:167], v[52:55]
	v_mfma_f32_16x16x32_bf16 v[52:55], v[136:139], v[168:171], v[52:55]
	v_mfma_f32_16x16x32_bf16 v[36:39], v[112:115], v[172:175], v[36:39]
	v_mfma_f32_16x16x32_bf16 v[36:39], v[136:139], v[176:179], v[36:39]
	v_mfma_f32_16x16x32_bf16 v[20:23], v[112:115], v[180:183], v[20:23]
	v_mfma_f32_16x16x32_bf16 v[20:23], v[136:139], v[184:187], v[20:23]
	v_mfma_f32_16x16x32_bf16 v[4:7], v[112:115], v[188:191], v[4:7]
	v_mfma_f32_16x16x32_bf16 v[4:7], v[136:139], v[192:195], v[4:7]
	v_mfma_f32_16x16x32_bf16 v[0:3], v[148:151], v[188:191], v[0:3]
	v_mfma_f32_16x16x32_bf16 v[0:3], v[160:163], v[192:195], v[0:3]
	v_mfma_f32_16x16x32_bf16 v[16:19], v[148:151], v[180:183], v[16:19]
	v_mfma_f32_16x16x32_bf16 v[16:19], v[160:163], v[184:187], v[16:19]
	v_mfma_f32_16x16x32_bf16 v[32:35], v[148:151], v[172:175], v[32:35]
	v_mfma_f32_16x16x32_bf16 v[32:35], v[160:163], v[176:179], v[32:35]
	v_mfma_f32_16x16x32_bf16 v[48:51], v[148:151], v[164:167], v[48:51]
	s_barrier
	v_mfma_f32_16x16x32_bf16 v[48:51], v[160:163], v[168:171], v[48:51]
	s_setprio 0
	ds_read_b128 v[72:75], v124
	ds_read_b128 v[84:87], v124 offset:1024
	ds_read_b128 v[96:99], v124 offset:2048
	ds_read_b128 v[108:111], v124 offset:3072
	ds_read_b128 v[112:115], v125
	ds_read_b128 v[136:139], v125 offset:1024
	ds_read_b128 v[148:151], v125 offset:2048
	ds_read_b128 v[160:163], v125 offset:3072
	ds_read_b128 v[164:167], v214 offset:32768
	ds_read_b128 v[168:171], v214 offset:33792
	ds_read_b128 v[172:175], v214 offset:34816
	ds_read_b128 v[176:179], v214 offset:35840
	ds_read_b128 v[180:183], v214 offset:36864
	ds_read_b128 v[184:187], v214 offset:37888
	ds_read_b128 v[188:191], v214 offset:38912
	ds_read_b128 v[192:195], v214 offset:39936
	s_add_u32 s92, s2, 0x4000
	s_addc_u32 s93, s3, 0
	s_mov_b32 m0, s64
	s_nop 0
	global_load_lds_dwordx4 v210, s[92:93]
	s_add_u32 s92, s2, 0x6000
	s_addc_u32 s93, s3, 0
	s_mov_b32 m0, s65
	s_nop 0
	global_load_lds_dwordx4 v210, s[92:93]
	s_waitcnt vmcnt(8)
	s_waitcnt lgkmcnt(0)
	s_barrier
	s_setprio 1
	s_waitcnt lgkmcnt(7)
	v_mfma_f32_16x16x32_bf16 v[156:159], v[72:75], v[164:167], v[156:159]
	v_mfma_f32_16x16x32_bf16 v[152:155], v[96:99], v[164:167], v[152:155]
	s_waitcnt lgkmcnt(5)
	v_mfma_f32_16x16x32_bf16 v[130:133], v[72:75], v[172:175], v[132:135]
	v_mfma_f32_16x16x32_bf16 v[126:129], v[96:99], v[172:175], v[126:129]
	s_waitcnt lgkmcnt(3)
	v_mfma_f32_16x16x32_bf16 v[104:107], v[72:75], v[180:183], v[104:107]
	v_mfma_f32_16x16x32_bf16 v[100:103], v[96:99], v[180:183], v[100:103]
	s_waitcnt lgkmcnt(1)
	v_mfma_f32_16x16x32_bf16 v[80:83], v[72:75], v[188:191], v[80:83]
	v_mfma_f32_16x16x32_bf16 v[76:79], v[96:99], v[188:191], v[76:79]
	v_mfma_f32_16x16x32_bf16 v[156:159], v[84:87], v[168:171], v[156:159]
	v_mfma_f32_16x16x32_bf16 v[152:155], v[108:111], v[168:171], v[152:155]
	v_mfma_f32_16x16x32_bf16 v[132:135], v[84:87], v[176:179], v[130:133]
	v_mfma_f32_16x16x32_bf16 v[128:131], v[108:111], v[176:179], v[126:129]
	v_mfma_f32_16x16x32_bf16 v[104:107], v[84:87], v[184:187], v[104:107]
	v_mfma_f32_16x16x32_bf16 v[100:103], v[108:111], v[184:187], v[100:103]
	s_waitcnt lgkmcnt(0)
	v_mfma_f32_16x16x32_bf16 v[80:83], v[84:87], v[192:195], v[80:83]
	v_mfma_f32_16x16x32_bf16 v[76:79], v[108:111], v[192:195], v[76:79]
	s_setprio 0
	s_setprio 1
	s_waitcnt lgkmcnt(0)
	v_mfma_f32_16x16x32_bf16 v[144:147], v[112:115], v[164:167], v[144:147]
	v_mfma_f32_16x16x32_bf16 v[144:147], v[136:139], v[168:171], v[144:147]
	v_mfma_f32_16x16x32_bf16 v[120:123], v[112:115], v[172:175], v[120:123]
	v_mfma_f32_16x16x32_bf16 v[120:123], v[136:139], v[176:179], v[120:123]
	v_mfma_f32_16x16x32_bf16 v[92:95], v[112:115], v[180:183], v[92:95]
	v_mfma_f32_16x16x32_bf16 v[92:95], v[136:139], v[184:187], v[92:95]
	v_mfma_f32_16x16x32_bf16 v[68:71], v[112:115], v[188:191], v[68:71]
	v_mfma_f32_16x16x32_bf16 v[68:71], v[136:139], v[192:195], v[68:71]
	v_mfma_f32_16x16x32_bf16 v[64:67], v[148:151], v[188:191], v[64:67]
	v_mfma_f32_16x16x32_bf16 v[64:67], v[160:163], v[192:195], v[64:67]
	v_mfma_f32_16x16x32_bf16 v[88:91], v[148:151], v[180:183], v[88:91]
	v_mfma_f32_16x16x32_bf16 v[88:91], v[160:163], v[184:187], v[88:91]
	v_mfma_f32_16x16x32_bf16 v[116:119], v[148:151], v[172:175], v[116:119]
	v_mfma_f32_16x16x32_bf16 v[116:119], v[160:163], v[176:179], v[116:119]
	v_mfma_f32_16x16x32_bf16 v[140:143], v[148:151], v[164:167], v[140:143]
	s_barrier
	v_mfma_f32_16x16x32_bf16 v[140:143], v[160:163], v[168:171], v[140:143]
	s_setprio 0
	ds_read_b128 v[164:167], v214 offset:49152
	ds_read_b128 v[168:171], v214 offset:50176
	ds_read_b128 v[172:175], v214 offset:51200
	ds_read_b128 v[176:179], v214 offset:52224
	ds_read_b128 v[180:183], v214 offset:53248
	ds_read_b128 v[184:187], v214 offset:54272
	ds_read_b128 v[188:191], v214 offset:55296
	ds_read_b128 v[192:195], v214 offset:56320
	s_mov_b32 m0, s69
	s_nop 0
	global_load_lds_dwordx4 v210, s[52:53]
	s_add_u32 s52, s58, 0xa000
	s_addc_u32 s53, s59, 0
	s_mov_b32 m0, s70
	s_nop 0
	global_load_lds_dwordx4 v210, s[52:53]
	s_add_u32 s52, s58, 0xc000
	s_addc_u32 s53, s59, 0
	s_mov_b32 m0, s73
	s_nop 0
	global_load_lds_dwordx4 v210, s[52:53]
	s_add_u32 s52, s58, 0xe000
	s_addc_u32 s53, s59, 0
	s_mov_b32 m0, s74
	s_nop 0
	global_load_lds_dwordx4 v210, s[52:53]
	s_add_u32 s2, s2, 0xa000
	s_mov_b32 m0, s71
	s_nop 0
	global_load_lds_dwordx4 v210, s[56:57]
	s_addc_u32 s3, s3, 0
	s_mov_b32 m0, s72
	s_nop 0
	global_load_lds_dwordx4 v210, s[2:3]
	s_waitcnt vmcnt(8)
	s_waitcnt lgkmcnt(0)
	s_barrier
	s_setprio 1
	s_waitcnt lgkmcnt(7)
	s_waitcnt lgkmcnt(0)
	v_mfma_f32_16x16x32_bf16 v[60:63], v[72:75], v[164:167], v[60:63]
	v_mfma_f32_16x16x32_bf16 v[60:63], v[84:87], v[168:171], v[60:63]
	v_mfma_f32_16x16x32_bf16 v[44:47], v[72:75], v[172:175], v[44:47]
	v_mfma_f32_16x16x32_bf16 v[44:47], v[84:87], v[176:179], v[44:47]
	v_mfma_f32_16x16x32_bf16 v[28:31], v[72:75], v[180:183], v[28:31]
	v_mfma_f32_16x16x32_bf16 v[28:31], v[84:87], v[184:187], v[28:31]
	v_mfma_f32_16x16x32_bf16 v[12:15], v[72:75], v[188:191], v[12:15]
	v_mfma_f32_16x16x32_bf16 v[12:15], v[84:87], v[192:195], v[12:15]
	v_mfma_f32_16x16x32_bf16 v[8:11], v[96:99], v[188:191], v[8:11]
	v_mfma_f32_16x16x32_bf16 v[8:11], v[108:111], v[192:195], v[8:11]
	v_mfma_f32_16x16x32_bf16 v[24:27], v[96:99], v[180:183], v[24:27]
	v_mfma_f32_16x16x32_bf16 v[24:27], v[108:111], v[184:187], v[24:27]
	v_mfma_f32_16x16x32_bf16 v[40:43], v[96:99], v[172:175], v[40:43]
	v_mfma_f32_16x16x32_bf16 v[40:43], v[108:111], v[176:179], v[40:43]
	v_mfma_f32_16x16x32_bf16 v[56:59], v[96:99], v[164:167], v[56:59]
	v_mfma_f32_16x16x32_bf16 v[56:59], v[108:111], v[168:171], v[56:59]
	s_setprio 0
	s_setprio 1
	s_waitcnt lgkmcnt(0)
	v_mfma_f32_16x16x32_bf16 v[52:55], v[112:115], v[164:167], v[52:55]
	v_mfma_f32_16x16x32_bf16 v[52:55], v[136:139], v[168:171], v[52:55]
	v_mfma_f32_16x16x32_bf16 v[36:39], v[112:115], v[172:175], v[36:39]
	v_mfma_f32_16x16x32_bf16 v[36:39], v[136:139], v[176:179], v[36:39]
	v_mfma_f32_16x16x32_bf16 v[20:23], v[112:115], v[180:183], v[20:23]
	v_mfma_f32_16x16x32_bf16 v[20:23], v[136:139], v[184:187], v[20:23]
	v_mfma_f32_16x16x32_bf16 v[4:7], v[112:115], v[188:191], v[4:7]
	v_mfma_f32_16x16x32_bf16 v[4:7], v[136:139], v[192:195], v[4:7]
	v_mfma_f32_16x16x32_bf16 v[0:3], v[148:151], v[188:191], v[0:3]
	v_mfma_f32_16x16x32_bf16 v[0:3], v[160:163], v[192:195], v[0:3]
	v_mfma_f32_16x16x32_bf16 v[16:19], v[148:151], v[180:183], v[16:19]
	v_mfma_f32_16x16x32_bf16 v[16:19], v[160:163], v[184:187], v[16:19]
	v_mfma_f32_16x16x32_bf16 v[32:35], v[148:151], v[172:175], v[32:35]
	v_mfma_f32_16x16x32_bf16 v[32:35], v[160:163], v[176:179], v[32:35]
	v_mfma_f32_16x16x32_bf16 v[48:51], v[148:151], v[164:167], v[48:51]
	s_barrier
	v_mfma_f32_16x16x32_bf16 v[48:51], v[160:163], v[168:171], v[48:51]
	s_setprio 0
	s_nop 7
	s_add_i32 s90, s90, 2
	s_add_u32 s54, s54, 0x10000
	s_addc_u32 s55, s55, 0
	s_add_u32 s88, s88, 0x10000
	s_addc_u32 s89, s89, 0
	s_cmp_gt_u32 s90, 61
	s_cbranch_scc0 .LBB0_1406
	s_and_b64 vcc, exec, s[12:13]
	s_cbranch_vccz .LBB0_1409
	s_barrier

.LBB0_1505:
	ds_read_b128 v[128:131], v156
	ds_read_b128 v[132:135], v156 offset:1024
	ds_read_b128 v[136:139], v156 offset:2048
	ds_read_b128 v[140:143], v156 offset:3072
	ds_read_b128 v[146:149], v157
	ds_read_b128 v[162:165], v157 offset:1024
	ds_read_b128 v[166:169], v157 offset:2048
	ds_read_b128 v[170:173], v157 offset:3072
	s_add_u32 s2, s52, 0x10000
	s_addc_u32 s3, s53, 0
	s_cmp_eq_u32 s96, 60
	s_cselect_b32 s58, s92, s2
	s_cselect_b32 s59, s45, s3
	s_cselect_b32 s64, s93, s54
	s_cselect_b32 s65, s43, s55
	s_add_u32 s60, s58, 0x8000
	s_addc_u32 s61, s59, 0
	ds_read_b128 v[174:177], v158
	ds_read_b128 v[178:181], v158 offset:1024
	ds_read_b128 v[182:185], v158 offset:2048
	ds_read_b128 v[186:189], v158 offset:3072
	ds_read_b128 v[190:193], v158 offset:4096
	ds_read_b128 v[194:197], v158 offset:5120
	ds_read_b128 v[198:201], v158 offset:6144
	ds_read_b128 v[202:205], v158 offset:7168
	s_add_u32 s12, s52, 0xc000
	s_addc_u32 s13, s53, 0
	s_mov_b32 m0, s81
	s_nop 0
	global_load_lds_dwordx4 v154, s[12:13]
	s_add_u32 s12, s52, 0xe000
	s_addc_u32 s13, s53, 0
	s_mov_b32 m0, s82
	s_nop 0
	global_load_lds_dwordx4 v154, s[12:13]
	s_waitcnt vmcnt(8)
	s_waitcnt lgkmcnt(0)
	s_add_u32 s52, s64, 0x8000
	s_addc_u32 s53, s65, 0
	s_barrier
	s_setprio 1
	s_waitcnt lgkmcnt(7)
	s_waitcnt lgkmcnt(0)
	v_mfma_f32_16x16x32_bf16 v[116:119], v[128:131], v[174:177], v[116:119]
	v_mfma_f32_16x16x32_bf16 v[116:119], v[132:135], v[178:181], v[116:119]
	v_mfma_f32_16x16x32_bf16 v[100:103], v[128:131], v[182:185], v[100:103]
	v_mfma_f32_16x16x32_bf16 v[100:103], v[132:135], v[186:189], v[100:103]
	v_mfma_f32_16x16x32_bf16 v[92:95], v[128:131], v[190:193], v[92:95]
	v_mfma_f32_16x16x32_bf16 v[92:95], v[132:135], v[194:197], v[92:95]
	v_mfma_f32_16x16x32_bf16 v[76:79], v[128:131], v[198:201], v[76:79]
	v_mfma_f32_16x16x32_bf16 v[76:79], v[132:135], v[202:205], v[76:79]
	v_mfma_f32_16x16x32_bf16 v[72:75], v[136:139], v[198:201], v[72:75]
	v_mfma_f32_16x16x32_bf16 v[72:75], v[140:143], v[202:205], v[72:75]
	v_mfma_f32_16x16x32_bf16 v[88:91], v[136:139], v[190:193], v[88:91]
	v_mfma_f32_16x16x32_bf16 v[88:91], v[140:143], v[194:197], v[88:91]
	v_mfma_f32_16x16x32_bf16 v[96:99], v[136:139], v[182:185], v[96:99]
	v_mfma_f32_16x16x32_bf16 v[96:99], v[140:143], v[186:189], v[96:99]
	v_mfma_f32_16x16x32_bf16 v[112:115], v[136:139], v[174:177], v[112:115]
	v_mfma_f32_16x16x32_bf16 v[112:115], v[140:143], v[178:181], v[112:115]
	s_setprio 0
	s_setprio 1
	s_waitcnt lgkmcnt(0)
	v_mfma_f32_16x16x32_bf16 v[124:127], v[146:149], v[174:177], v[124:127]
	v_mfma_f32_16x16x32_bf16 v[124:127], v[162:165], v[178:181], v[124:127]
	v_mfma_f32_16x16x32_bf16 v[108:111], v[146:149], v[182:185], v[108:111]
	v_mfma_f32_16x16x32_bf16 v[108:111], v[162:165], v[186:189], v[108:111]
	v_mfma_f32_16x16x32_bf16 v[84:87], v[146:149], v[190:193], v[84:87]
	v_mfma_f32_16x16x32_bf16 v[84:87], v[162:165], v[194:197], v[84:87]
	v_mfma_f32_16x16x32_bf16 v[68:71], v[146:149], v[198:201], v[68:71]
	v_mfma_f32_16x16x32_bf16 v[68:71], v[162:165], v[202:205], v[68:71]
	v_mfma_f32_16x16x32_bf16 v[64:67], v[166:169], v[198:201], v[64:67]
	v_mfma_f32_16x16x32_bf16 v[64:67], v[170:173], v[202:205], v[64:67]
	v_mfma_f32_16x16x32_bf16 v[80:83], v[166:169], v[190:193], v[80:83]
	v_mfma_f32_16x16x32_bf16 v[80:83], v[170:173], v[194:197], v[80:83]
	v_mfma_f32_16x16x32_bf16 v[104:107], v[166:169], v[182:185], v[104:107]
	v_mfma_f32_16x16x32_bf16 v[104:107], v[170:173], v[186:189], v[104:107]
	v_mfma_f32_16x16x32_bf16 v[120:123], v[166:169], v[174:177], v[120:123]
	s_barrier
	v_mfma_f32_16x16x32_bf16 v[120:123], v[170:173], v[178:181], v[120:123]
	s_setprio 0
	s_add_u32 s12, s64, 0x2000
	ds_read_b128 v[174:177], v158 offset:16384
	ds_read_b128 v[178:181], v158 offset:17408
	ds_read_b128 v[182:185], v158 offset:18432
	ds_read_b128 v[186:189], v158 offset:19456
	ds_read_b128 v[190:193], v158 offset:20480
	ds_read_b128 v[194:197], v158 offset:21504
	ds_read_b128 v[198:201], v158 offset:22528
	ds_read_b128 v[202:205], v158 offset:23552
	s_mov_b32 m0, s57
	s_nop 0
	global_load_lds_dwordx4 v154, s[64:65]
	s_addc_u32 s13, s65, 0
	s_mov_b32 m0, s67
	s_nop 0
	global_load_lds_dwordx4 v154, s[12:13]
	s_add_u32 s12, s64, 0x4000
	s_addc_u32 s13, s65, 0
	s_mov_b32 m0, s68
	s_nop 0
	global_load_lds_dwordx4 v154, s[12:13]
	s_add_u32 s12, s64, 0x6000
	s_addc_u32 s13, s65, 0
	s_mov_b32 m0, s69
	s_nop 0
	global_load_lds_dwordx4 v154, s[12:13]
	s_add_u32 s12, s58, 0x2000
	s_mov_b32 m0, s66
	s_nop 0
	global_load_lds_dwordx4 v154, s[58:59]
	s_addc_u32 s13, s59, 0
	s_mov_b32 m0, s70
	s_nop 0
	global_load_lds_dwordx4 v154, s[12:13]
	s_waitcnt vmcnt(8)
	s_waitcnt lgkmcnt(0)
	s_barrier
	s_setprio 1
	s_waitcnt lgkmcnt(7)
	s_waitcnt lgkmcnt(0)
	v_mfma_f32_16x16x32_bf16 v[60:63], v[128:131], v[174:177], v[60:63]
	v_mfma_f32_16x16x32_bf16 v[60:63], v[132:135], v[178:181], v[60:63]
	v_mfma_f32_16x16x32_bf16 v[44:47], v[128:131], v[182:185], v[44:47]
	v_mfma_f32_16x16x32_bf16 v[44:47], v[132:135], v[186:189], v[44:47]
	v_mfma_f32_16x16x32_bf16 v[28:31], v[128:131], v[190:193], v[28:31]
	v_mfma_f32_16x16x32_bf16 v[28:31], v[132:135], v[194:197], v[28:31]
	v_mfma_f32_16x16x32_bf16 v[12:15], v[128:131], v[198:201], v[12:15]
	v_mfma_f32_16x16x32_bf16 v[12:15], v[132:135], v[202:205], v[12:15]
	v_mfma_f32_16x16x32_bf16 v[8:11], v[136:139], v[198:201], v[8:11]
	v_mfma_f32_16x16x32_bf16 v[8:11], v[140:143], v[202:205], v[8:11]
	v_mfma_f32_16x16x32_bf16 v[24:27], v[136:139], v[190:193], v[24:27]
	v_mfma_f32_16x16x32_bf16 v[24:27], v[140:143], v[194:197], v[24:27]
	v_mfma_f32_16x16x32_bf16 v[40:43], v[136:139], v[182:185], v[40:43]
	v_mfma_f32_16x16x32_bf16 v[40:43], v[140:143], v[186:189], v[40:43]
	v_mfma_f32_16x16x32_bf16 v[56:59], v[136:139], v[174:177], v[56:59]
	v_mfma_f32_16x16x32_bf16 v[56:59], v[140:143], v[178:181], v[56:59]
	s_setprio 0
	s_setprio 1
	s_waitcnt lgkmcnt(0)
	v_mfma_f32_16x16x32_bf16 v[52:55], v[146:149], v[174:177], v[52:55]
	v_mfma_f32_16x16x32_bf16 v[52:55], v[162:165], v[178:181], v[52:55]
	v_mfma_f32_16x16x32_bf16 v[36:39], v[146:149], v[182:185], v[36:39]
	v_mfma_f32_16x16x32_bf16 v[36:39], v[162:165], v[186:189], v[36:39]
	v_mfma_f32_16x16x32_bf16 v[20:23], v[146:149], v[190:193], v[20:23]
	v_mfma_f32_16x16x32_bf16 v[20:23], v[162:165], v[194:197], v[20:23]
	v_mfma_f32_16x16x32_bf16 v[4:7], v[146:149], v[198:201], v[4:7]
	v_mfma_f32_16x16x32_bf16 v[4:7], v[162:165], v[202:205], v[4:7]
	v_mfma_f32_16x16x32_bf16 v[0:3], v[166:169], v[198:201], v[0:3]
	v_mfma_f32_16x16x32_bf16 v[0:3], v[170:173], v[202:205], v[0:3]
	v_mfma_f32_16x16x32_bf16 v[16:19], v[166:169], v[190:193], v[16:19]
	v_mfma_f32_16x16x32_bf16 v[16:19], v[170:173], v[194:197], v[16:19]
	v_mfma_f32_16x16x32_bf16 v[32:35], v[166:169], v[182:185], v[32:35]
	v_mfma_f32_16x16x32_bf16 v[32:35], v[170:173], v[186:189], v[32:35]
	v_mfma_f32_16x16x32_bf16 v[48:51], v[166:169], v[174:177], v[48:51]
	s_barrier
	v_mfma_f32_16x16x32_bf16 v[48:51], v[170:173], v[178:181], v[48:51]
	s_setprio 0
	ds_read_b128 v[128:131], v144
	ds_read_b128 v[132:135], v144 offset:1024
	ds_read_b128 v[136:139], v144 offset:2048
	ds_read_b128 v[140:143], v144 offset:3072
	ds_read_b128 v[146:149], v150
	ds_read_b128 v[162:165], v150 offset:1024
	ds_read_b128 v[166:169], v150 offset:2048
	ds_read_b128 v[170:173], v150 offset:3072
	ds_read_b128 v[174:177], v158 offset:32768
	ds_read_b128 v[178:181], v158 offset:33792
	ds_read_b128 v[182:185], v158 offset:34816
	ds_read_b128 v[186:189], v158 offset:35840
	ds_read_b128 v[190:193], v158 offset:36864
	ds_read_b128 v[194:197], v158 offset:37888
	ds_read_b128 v[198:201], v158 offset:38912
	ds_read_b128 v[202:205], v158 offset:39936
	s_add_u32 s12, s58, 0x4000
	s_addc_u32 s13, s59, 0
	s_mov_b32 m0, s71
	s_nop 0
	global_load_lds_dwordx4 v154, s[12:13]
	s_add_u32 s12, s58, 0x6000
	s_addc_u32 s13, s59, 0
	s_mov_b32 m0, s72
	s_nop 0
	global_load_lds_dwordx4 v154, s[12:13]
	s_waitcnt vmcnt(8)
	s_waitcnt lgkmcnt(0)
	s_barrier
	s_setprio 1
	s_waitcnt lgkmcnt(7)
	s_waitcnt lgkmcnt(0)
	v_mfma_f32_16x16x32_bf16 v[116:119], v[128:131], v[174:177], v[116:119]
	v_mfma_f32_16x16x32_bf16 v[116:119], v[132:135], v[178:181], v[116:119]
	v_mfma_f32_16x16x32_bf16 v[100:103], v[128:131], v[182:185], v[100:103]
	v_mfma_f32_16x16x32_bf16 v[100:103], v[132:135], v[186:189], v[100:103]
	v_mfma_f32_16x16x32_bf16 v[92:95], v[128:131], v[190:193], v[92:95]
	v_mfma_f32_16x16x32_bf16 v[92:95], v[132:135], v[194:197], v[92:95]
	v_mfma_f32_16x16x32_bf16 v[76:79], v[128:131], v[198:201], v[76:79]
	v_mfma_f32_16x16x32_bf16 v[76:79], v[132:135], v[202:205], v[76:79]
	v_mfma_f32_16x16x32_bf16 v[72:75], v[136:139], v[198:201], v[72:75]
	v_mfma_f32_16x16x32_bf16 v[72:75], v[140:143], v[202:205], v[72:75]
	v_mfma_f32_16x16x32_bf16 v[88:91], v[136:139], v[190:193], v[88:91]
	v_mfma_f32_16x16x32_bf16 v[88:91], v[140:143], v[194:197], v[88:91]
	v_mfma_f32_16x16x32_bf16 v[96:99], v[136:139], v[182:185], v[96:99]
	v_mfma_f32_16x16x32_bf16 v[96:99], v[140:143], v[186:189], v[96:99]
	v_mfma_f32_16x16x32_bf16 v[112:115], v[136:139], v[174:177], v[112:115]
	v_mfma_f32_16x16x32_bf16 v[112:115], v[140:143], v[178:181], v[112:115]
	s_setprio 0
	s_setprio 1
	s_waitcnt lgkmcnt(0)
	v_mfma_f32_16x16x32_bf16 v[124:127], v[146:149], v[174:177], v[124:127]
	v_mfma_f32_16x16x32_bf16 v[124:127], v[162:165], v[178:181], v[124:127]
	v_mfma_f32_16x16x32_bf16 v[108:111], v[146:149], v[182:185], v[108:111]
	v_mfma_f32_16x16x32_bf16 v[108:111], v[162:165], v[186:189], v[108:111]
	v_mfma_f32_16x16x32_bf16 v[84:87], v[146:149], v[190:193], v[84:87]
	v_mfma_f32_16x16x32_bf16 v[84:87], v[162:165], v[194:197], v[84:87]
	v_mfma_f32_16x16x32_bf16 v[68:71], v[146:149], v[198:201], v[68:71]
	v_mfma_f32_16x16x32_bf16 v[68:71], v[162:165], v[202:205], v[68:71]
	v_mfma_f32_16x16x32_bf16 v[64:67], v[166:169], v[198:201], v[64:67]
	v_mfma_f32_16x16x32_bf16 v[64:67], v[170:173], v[202:205], v[64:67]
	v_mfma_f32_16x16x32_bf16 v[80:83], v[166:169], v[190:193], v[80:83]
	v_mfma_f32_16x16x32_bf16 v[80:83], v[170:173], v[194:197], v[80:83]
	v_mfma_f32_16x16x32_bf16 v[104:107], v[166:169], v[182:185], v[104:107]
	v_mfma_f32_16x16x32_bf16 v[104:107], v[170:173], v[186:189], v[104:107]
	v_mfma_f32_16x16x32_bf16 v[120:123], v[166:169], v[174:177], v[120:123]
	s_barrier
	v_mfma_f32_16x16x32_bf16 v[120:123], v[170:173], v[178:181], v[120:123]
	s_setprio 0
	s_add_u32 s12, s64, 0xa000
	ds_read_b128 v[174:177], v158 offset:49152
	ds_read_b128 v[178:181], v158 offset:50176
	ds_read_b128 v[182:185], v158 offset:51200
	ds_read_b128 v[186:189], v158 offset:52224
	ds_read_b128 v[190:193], v158 offset:53248
	ds_read_b128 v[194:197], v158 offset:54272
	ds_read_b128 v[198:201], v158 offset:55296
	ds_read_b128 v[202:205], v158 offset:56320
	s_mov_b32 m0, s75
	s_nop 0
	global_load_lds_dwordx4 v154, s[52:53]
	s_addc_u32 s13, s65, 0
	s_mov_b32 m0, s76
	s_nop 0
	global_load_lds_dwordx4 v154, s[12:13]
	s_add_u32 s12, s64, 0xc000
	s_addc_u32 s13, s65, 0
	s_mov_b32 m0, s79
	s_nop 0
	global_load_lds_dwordx4 v154, s[12:13]
	s_add_u32 s12, s64, 0xe000
	s_addc_u32 s13, s65, 0
	s_mov_b32 m0, s80
	s_nop 0
	global_load_lds_dwordx4 v154, s[12:13]
	s_add_u32 s12, s58, 0xa000
	s_mov_b32 m0, s77
	s_nop 0
	global_load_lds_dwordx4 v154, s[60:61]
	s_addc_u32 s13, s59, 0
	s_mov_b32 m0, s78
	s_nop 0
	global_load_lds_dwordx4 v154, s[12:13]
	s_waitcnt vmcnt(8)
	s_waitcnt lgkmcnt(0)
	s_barrier
	s_setprio 1
	s_waitcnt lgkmcnt(7)
	s_waitcnt lgkmcnt(0)
	v_mfma_f32_16x16x32_bf16 v[60:63], v[128:131], v[174:177], v[60:63]
	v_mfma_f32_16x16x32_bf16 v[60:63], v[132:135], v[178:181], v[60:63]
	v_mfma_f32_16x16x32_bf16 v[44:47], v[128:131], v[182:185], v[44:47]
	v_mfma_f32_16x16x32_bf16 v[44:47], v[132:135], v[186:189], v[44:47]
	v_mfma_f32_16x16x32_bf16 v[28:31], v[128:131], v[190:193], v[28:31]
	v_mfma_f32_16x16x32_bf16 v[28:31], v[132:135], v[194:197], v[28:31]
	v_mfma_f32_16x16x32_bf16 v[12:15], v[128:131], v[198:201], v[12:15]
	v_mfma_f32_16x16x32_bf16 v[12:15], v[132:135], v[202:205], v[12:15]
	v_mfma_f32_16x16x32_bf16 v[8:11], v[136:139], v[198:201], v[8:11]
	v_mfma_f32_16x16x32_bf16 v[8:11], v[140:143], v[202:205], v[8:11]
	v_mfma_f32_16x16x32_bf16 v[24:27], v[136:139], v[190:193], v[24:27]
	v_mfma_f32_16x16x32_bf16 v[24:27], v[140:143], v[194:197], v[24:27]
	v_mfma_f32_16x16x32_bf16 v[40:43], v[136:139], v[182:185], v[40:43]
	v_mfma_f32_16x16x32_bf16 v[40:43], v[140:143], v[186:189], v[40:43]
	v_mfma_f32_16x16x32_bf16 v[56:59], v[136:139], v[174:177], v[56:59]
	v_mfma_f32_16x16x32_bf16 v[56:59], v[140:143], v[178:181], v[56:59]
	s_setprio 0
	s_setprio 1
	s_waitcnt lgkmcnt(0)
	v_mfma_f32_16x16x32_bf16 v[52:55], v[146:149], v[174:177], v[52:55]
	v_mfma_f32_16x16x32_bf16 v[52:55], v[162:165], v[178:181], v[52:55]
	v_mfma_f32_16x16x32_bf16 v[36:39], v[146:149], v[182:185], v[36:39]
	v_mfma_f32_16x16x32_bf16 v[36:39], v[162:165], v[186:189], v[36:39]
	v_mfma_f32_16x16x32_bf16 v[20:23], v[146:149], v[190:193], v[20:23]
	v_mfma_f32_16x16x32_bf16 v[20:23], v[162:165], v[194:197], v[20:23]
	v_mfma_f32_16x16x32_bf16 v[4:7], v[146:149], v[198:201], v[4:7]
	v_mfma_f32_16x16x32_bf16 v[4:7], v[162:165], v[202:205], v[4:7]
	v_mfma_f32_16x16x32_bf16 v[0:3], v[166:169], v[198:201], v[0:3]
	v_mfma_f32_16x16x32_bf16 v[0:3], v[170:173], v[202:205], v[0:3]
	v_mfma_f32_16x16x32_bf16 v[16:19], v[166:169], v[190:193], v[16:19]
	v_mfma_f32_16x16x32_bf16 v[16:19], v[170:173], v[194:197], v[16:19]
	v_mfma_f32_16x16x32_bf16 v[32:35], v[166:169], v[182:185], v[32:35]
	v_mfma_f32_16x16x32_bf16 v[32:35], v[170:173], v[186:189], v[32:35]
	v_mfma_f32_16x16x32_bf16 v[48:51], v[166:169], v[174:177], v[48:51]
	s_barrier
	v_mfma_f32_16x16x32_bf16 v[48:51], v[170:173], v[178:181], v[48:51]
	s_setprio 0
	s_nop 7
	s_add_i32 s96, s96, 2
	s_add_u32 s54, s54, 0x10000
	s_addc_u32 s55, s55, 0
	s_cmp_gt_u32 s96, 61
	s_mov_b64 s[52:53], s[2:3]
	s_cbranch_scc0 .LBB0_1505
	s_and_b64 vcc, exec, s[40:41]
	s_cbranch_vccz .LBB0_1508
	s_barrier

.LBB0_1539:
	ds_read_b128 v[128:131], v138
	ds_read_b128 v[132:135], v138 offset:1024
	ds_read_b128 v[144:147], v138 offset:2048
	ds_read_b128 v[148:151], v138 offset:3072
	ds_read_b128 v[152:155], v139
	ds_read_b128 v[156:159], v139 offset:1024
	ds_read_b128 v[160:163], v139 offset:2048
	ds_read_b128 v[164:167], v139 offset:3072
	s_add_u32 s2, s52, 0x10000
	s_addc_u32 s3, s53, 0
	s_cmp_eq_u32 s83, 60
	s_cselect_b32 s46, s79, s2
	s_cselect_b32 s47, s39, s3
	s_cselect_b32 s56, s80, s81
	s_cselect_b32 s57, s15, s82
	s_add_u32 s48, s46, 0x8000
	s_addc_u32 s49, s47, 0
	ds_read_b128 v[168:171], v140
	ds_read_b128 v[172:175], v140 offset:1024
	ds_read_b128 v[176:179], v140 offset:2048
	ds_read_b128 v[180:183], v140 offset:3072
	ds_read_b128 v[184:187], v140 offset:4096
	ds_read_b128 v[188:191], v140 offset:5120
	ds_read_b128 v[192:195], v140 offset:6144
	ds_read_b128 v[196:199], v140 offset:7168
	s_add_u32 s88, s52, 0xc000
	s_addc_u32 s89, s53, 0
	s_mov_b32 m0, s74
	s_nop 0
	global_load_lds_dwordx4 v136, s[88:89]
	s_add_u32 s52, s52, 0xe000
	s_addc_u32 s53, s53, 0
	s_mov_b32 m0, s75
	s_nop 0
	global_load_lds_dwordx4 v136, s[52:53]
	s_waitcnt vmcnt(8)
	s_waitcnt lgkmcnt(0)
	s_add_u32 s52, s56, 0x8000
	s_addc_u32 s53, s57, 0
	s_barrier
	s_setprio 1
	s_waitcnt lgkmcnt(7)
	s_waitcnt lgkmcnt(0)
	v_mfma_f32_16x16x32_bf16 v[120:123], v[128:131], v[168:171], v[120:123]
	v_mfma_f32_16x16x32_bf16 v[120:123], v[132:135], v[172:175], v[120:123]
	v_mfma_f32_16x16x32_bf16 v[104:107], v[128:131], v[176:179], v[104:107]
	v_mfma_f32_16x16x32_bf16 v[104:107], v[132:135], v[180:183], v[104:107]
	v_mfma_f32_16x16x32_bf16 v[84:87], v[128:131], v[184:187], v[84:87]
	v_mfma_f32_16x16x32_bf16 v[84:87], v[132:135], v[188:191], v[84:87]
	v_mfma_f32_16x16x32_bf16 v[52:55], v[128:131], v[192:195], v[52:55]
	v_mfma_f32_16x16x32_bf16 v[52:55], v[132:135], v[196:199], v[52:55]
	v_mfma_f32_16x16x32_bf16 v[36:39], v[144:147], v[192:195], v[36:39]
	v_mfma_f32_16x16x32_bf16 v[36:39], v[148:151], v[196:199], v[36:39]
	v_mfma_f32_16x16x32_bf16 v[68:71], v[144:147], v[184:187], v[68:71]
	v_mfma_f32_16x16x32_bf16 v[68:71], v[148:151], v[188:191], v[68:71]
	v_mfma_f32_16x16x32_bf16 v[96:99], v[144:147], v[176:179], v[96:99]
	v_mfma_f32_16x16x32_bf16 v[96:99], v[148:151], v[180:183], v[96:99]
	v_mfma_f32_16x16x32_bf16 v[112:115], v[144:147], v[168:171], v[112:115]
	v_mfma_f32_16x16x32_bf16 v[112:115], v[148:151], v[172:175], v[112:115]
	s_setprio 0
	s_setprio 1
	s_waitcnt lgkmcnt(0)
	v_mfma_f32_16x16x32_bf16 v[124:127], v[152:155], v[168:171], v[124:127]
	v_mfma_f32_16x16x32_bf16 v[124:127], v[156:159], v[172:175], v[124:127]
	v_mfma_f32_16x16x32_bf16 v[108:111], v[152:155], v[176:179], v[108:111]
	v_mfma_f32_16x16x32_bf16 v[108:111], v[156:159], v[180:183], v[108:111]
	v_mfma_f32_16x16x32_bf16 v[88:91], v[152:155], v[184:187], v[88:91]
	v_mfma_f32_16x16x32_bf16 v[88:91], v[156:159], v[188:191], v[88:91]
	v_mfma_f32_16x16x32_bf16 v[56:59], v[152:155], v[192:195], v[56:59]
	v_mfma_f32_16x16x32_bf16 v[56:59], v[156:159], v[196:199], v[56:59]
	v_mfma_f32_16x16x32_bf16 v[40:43], v[160:163], v[192:195], v[40:43]
	v_mfma_f32_16x16x32_bf16 v[40:43], v[164:167], v[196:199], v[40:43]
	v_mfma_f32_16x16x32_bf16 v[72:75], v[160:163], v[184:187], v[72:75]
	v_mfma_f32_16x16x32_bf16 v[72:75], v[164:167], v[188:191], v[72:75]
	v_mfma_f32_16x16x32_bf16 v[100:103], v[160:163], v[176:179], v[100:103]
	v_mfma_f32_16x16x32_bf16 v[100:103], v[164:167], v[180:183], v[100:103]
	v_mfma_f32_16x16x32_bf16 v[116:119], v[160:163], v[168:171], v[116:119]
	s_barrier
	v_mfma_f32_16x16x32_bf16 v[116:119], v[164:167], v[172:175], v[116:119]
	s_setprio 0
	s_add_u32 s88, s56, 0x2000
	ds_read_b128 v[168:171], v140 offset:16384
	ds_read_b128 v[172:175], v140 offset:17408
	ds_read_b128 v[176:179], v140 offset:18432
	ds_read_b128 v[180:183], v140 offset:19456
	ds_read_b128 v[184:187], v140 offset:20480
	ds_read_b128 v[188:191], v140 offset:21504
	ds_read_b128 v[192:195], v140 offset:22528
	ds_read_b128 v[196:199], v140 offset:23552
	s_mov_b32 m0, s41
	s_nop 0
	global_load_lds_dwordx4 v136, s[56:57]
	s_addc_u32 s89, s57, 0
	s_mov_b32 m0, s59
	s_nop 0
	global_load_lds_dwordx4 v136, s[88:89]
	s_add_u32 s88, s56, 0x4000
	s_addc_u32 s89, s57, 0
	s_mov_b32 m0, s60
	s_nop 0
	global_load_lds_dwordx4 v136, s[88:89]
	s_add_u32 s88, s56, 0x6000
	s_addc_u32 s89, s57, 0
	s_mov_b32 m0, s61
	s_nop 0
	global_load_lds_dwordx4 v136, s[88:89]
	s_add_u32 s88, s46, 0x2000
	s_mov_b32 m0, s58
	s_nop 0
	global_load_lds_dwordx4 v136, s[46:47]
	s_addc_u32 s89, s47, 0
	s_mov_b32 m0, s62
	s_nop 0
	global_load_lds_dwordx4 v136, s[88:89]
	s_waitcnt vmcnt(8)
	s_waitcnt lgkmcnt(0)
	s_barrier
	s_setprio 1
	s_waitcnt lgkmcnt(7)
	s_waitcnt lgkmcnt(0)
	v_mfma_f32_16x16x32_bf16 v[92:95], v[128:131], v[168:171], v[92:95]
	v_mfma_f32_16x16x32_bf16 v[92:95], v[132:135], v[172:175], v[92:95]
	v_mfma_f32_16x16x32_bf16 v[60:63], v[128:131], v[176:179], v[60:63]
	v_mfma_f32_16x16x32_bf16 v[60:63], v[132:135], v[180:183], v[60:63]
	v_mfma_f32_16x16x32_bf16 v[28:31], v[128:131], v[184:187], v[28:31]
	v_mfma_f32_16x16x32_bf16 v[28:31], v[132:135], v[188:191], v[28:31]
	v_mfma_f32_16x16x32_bf16 v[12:15], v[128:131], v[192:195], v[12:15]
	v_mfma_f32_16x16x32_bf16 v[12:15], v[132:135], v[196:199], v[12:15]
	v_mfma_f32_16x16x32_bf16 v[8:11], v[144:147], v[192:195], v[8:11]
	v_mfma_f32_16x16x32_bf16 v[8:11], v[148:151], v[196:199], v[8:11]
	v_mfma_f32_16x16x32_bf16 v[24:27], v[144:147], v[184:187], v[24:27]
	v_mfma_f32_16x16x32_bf16 v[24:27], v[148:151], v[188:191], v[24:27]
	v_mfma_f32_16x16x32_bf16 v[48:51], v[144:147], v[176:179], v[48:51]
	v_mfma_f32_16x16x32_bf16 v[48:51], v[148:151], v[180:183], v[48:51]
	v_mfma_f32_16x16x32_bf16 v[80:83], v[144:147], v[168:171], v[80:83]
	v_mfma_f32_16x16x32_bf16 v[80:83], v[148:151], v[172:175], v[80:83]
	s_setprio 0
	s_setprio 1
	s_waitcnt lgkmcnt(0)
	v_mfma_f32_16x16x32_bf16 v[76:79], v[152:155], v[168:171], v[76:79]
	v_mfma_f32_16x16x32_bf16 v[76:79], v[156:159], v[172:175], v[76:79]
	v_mfma_f32_16x16x32_bf16 v[44:47], v[152:155], v[176:179], v[44:47]
	v_mfma_f32_16x16x32_bf16 v[44:47], v[156:159], v[180:183], v[44:47]
	v_mfma_f32_16x16x32_bf16 v[20:23], v[152:155], v[184:187], v[20:23]
	v_mfma_f32_16x16x32_bf16 v[20:23], v[156:159], v[188:191], v[20:23]
	v_mfma_f32_16x16x32_bf16 v[4:7], v[152:155], v[192:195], v[4:7]
	v_mfma_f32_16x16x32_bf16 v[4:7], v[156:159], v[196:199], v[4:7]
	v_mfma_f32_16x16x32_bf16 v[0:3], v[160:163], v[192:195], v[0:3]
	v_mfma_f32_16x16x32_bf16 v[0:3], v[164:167], v[196:199], v[0:3]
	v_mfma_f32_16x16x32_bf16 v[16:19], v[160:163], v[184:187], v[16:19]
	v_mfma_f32_16x16x32_bf16 v[16:19], v[164:167], v[188:191], v[16:19]
	v_mfma_f32_16x16x32_bf16 v[32:35], v[160:163], v[176:179], v[32:35]
	v_mfma_f32_16x16x32_bf16 v[32:35], v[164:167], v[180:183], v[32:35]
	v_mfma_f32_16x16x32_bf16 v[64:67], v[160:163], v[168:171], v[64:67]
	s_barrier
	v_mfma_f32_16x16x32_bf16 v[64:67], v[164:167], v[172:175], v[64:67]
	s_setprio 0
	ds_read_b128 v[128:131], v141
	ds_read_b128 v[132:135], v141 offset:1024
	ds_read_b128 v[144:147], v141 offset:2048
	ds_read_b128 v[148:151], v141 offset:3072
	ds_read_b128 v[152:155], v142
	ds_read_b128 v[156:159], v142 offset:1024
	ds_read_b128 v[160:163], v142 offset:2048
	ds_read_b128 v[164:167], v142 offset:3072
	ds_read_b128 v[168:171], v140 offset:32768
	ds_read_b128 v[172:175], v140 offset:33792
	ds_read_b128 v[176:179], v140 offset:34816
	ds_read_b128 v[180:183], v140 offset:35840
	ds_read_b128 v[184:187], v140 offset:36864
	ds_read_b128 v[188:191], v140 offset:37888
	ds_read_b128 v[192:195], v140 offset:38912
	ds_read_b128 v[196:199], v140 offset:39936
	s_add_u32 s88, s46, 0x4000
	s_addc_u32 s89, s47, 0
	s_mov_b32 m0, s63
	s_nop 0
	global_load_lds_dwordx4 v136, s[88:89]
	s_add_u32 s88, s46, 0x6000
	s_addc_u32 s89, s47, 0
	s_mov_b32 m0, s64
	s_nop 0
	global_load_lds_dwordx4 v136, s[88:89]
	s_waitcnt vmcnt(8)
	s_waitcnt lgkmcnt(0)
	s_barrier
	s_setprio 1
	s_waitcnt lgkmcnt(7)
	s_waitcnt lgkmcnt(0)
	v_mfma_f32_16x16x32_bf16 v[120:123], v[128:131], v[168:171], v[120:123]
	v_mfma_f32_16x16x32_bf16 v[120:123], v[132:135], v[172:175], v[120:123]
	v_mfma_f32_16x16x32_bf16 v[104:107], v[128:131], v[176:179], v[104:107]
	v_mfma_f32_16x16x32_bf16 v[104:107], v[132:135], v[180:183], v[104:107]
	v_mfma_f32_16x16x32_bf16 v[84:87], v[128:131], v[184:187], v[84:87]
	v_mfma_f32_16x16x32_bf16 v[84:87], v[132:135], v[188:191], v[84:87]
	v_mfma_f32_16x16x32_bf16 v[52:55], v[128:131], v[192:195], v[52:55]
	v_mfma_f32_16x16x32_bf16 v[52:55], v[132:135], v[196:199], v[52:55]
	v_mfma_f32_16x16x32_bf16 v[36:39], v[144:147], v[192:195], v[36:39]
	v_mfma_f32_16x16x32_bf16 v[36:39], v[148:151], v[196:199], v[36:39]
	v_mfma_f32_16x16x32_bf16 v[68:71], v[144:147], v[184:187], v[68:71]
	v_mfma_f32_16x16x32_bf16 v[68:71], v[148:151], v[188:191], v[68:71]
	v_mfma_f32_16x16x32_bf16 v[96:99], v[144:147], v[176:179], v[96:99]
	v_mfma_f32_16x16x32_bf16 v[96:99], v[148:151], v[180:183], v[96:99]
	v_mfma_f32_16x16x32_bf16 v[112:115], v[144:147], v[168:171], v[112:115]
	v_mfma_f32_16x16x32_bf16 v[112:115], v[148:151], v[172:175], v[112:115]
	s_setprio 0
	s_setprio 1
	s_waitcnt lgkmcnt(0)
	v_mfma_f32_16x16x32_bf16 v[124:127], v[152:155], v[168:171], v[124:127]
	v_mfma_f32_16x16x32_bf16 v[124:127], v[156:159], v[172:175], v[124:127]
	v_mfma_f32_16x16x32_bf16 v[108:111], v[152:155], v[176:179], v[108:111]
	v_mfma_f32_16x16x32_bf16 v[108:111], v[156:159], v[180:183], v[108:111]
	v_mfma_f32_16x16x32_bf16 v[88:91], v[152:155], v[184:187], v[88:91]
	v_mfma_f32_16x16x32_bf16 v[88:91], v[156:159], v[188:191], v[88:91]
	v_mfma_f32_16x16x32_bf16 v[56:59], v[152:155], v[192:195], v[56:59]
	v_mfma_f32_16x16x32_bf16 v[56:59], v[156:159], v[196:199], v[56:59]
	v_mfma_f32_16x16x32_bf16 v[40:43], v[160:163], v[192:195], v[40:43]
	v_mfma_f32_16x16x32_bf16 v[40:43], v[164:167], v[196:199], v[40:43]
	v_mfma_f32_16x16x32_bf16 v[72:75], v[160:163], v[184:187], v[72:75]
	v_mfma_f32_16x16x32_bf16 v[72:75], v[164:167], v[188:191], v[72:75]
	v_mfma_f32_16x16x32_bf16 v[100:103], v[160:163], v[176:179], v[100:103]
	v_mfma_f32_16x16x32_bf16 v[100:103], v[164:167], v[180:183], v[100:103]
	v_mfma_f32_16x16x32_bf16 v[116:119], v[160:163], v[168:171], v[116:119]
	s_barrier
	v_mfma_f32_16x16x32_bf16 v[116:119], v[164:167], v[172:175], v[116:119]
	s_setprio 0
	ds_read_b128 v[168:171], v140 offset:49152
	ds_read_b128 v[172:175], v140 offset:50176
	ds_read_b128 v[176:179], v140 offset:51200
	ds_read_b128 v[180:183], v140 offset:52224
	ds_read_b128 v[184:187], v140 offset:53248
	ds_read_b128 v[188:191], v140 offset:54272
	ds_read_b128 v[192:195], v140 offset:55296
	ds_read_b128 v[196:199], v140 offset:56320
	s_mov_b32 m0, s68
	s_nop 0
	global_load_lds_dwordx4 v136, s[52:53]
	s_add_u32 s52, s56, 0xa000
	s_addc_u32 s53, s57, 0
	s_mov_b32 m0, s69
	s_nop 0
	global_load_lds_dwordx4 v136, s[52:53]
	s_add_u32 s52, s56, 0xc000
	s_addc_u32 s53, s57, 0
	s_mov_b32 m0, s72
	s_nop 0
	global_load_lds_dwordx4 v136, s[52:53]
	s_add_u32 s52, s56, 0xe000
	s_addc_u32 s53, s57, 0
	s_mov_b32 m0, s73
	s_nop 0
	global_load_lds_dwordx4 v136, s[52:53]
	s_add_u32 s46, s46, 0xa000
	s_mov_b32 m0, s70
	s_nop 0
	global_load_lds_dwordx4 v136, s[48:49]
	s_addc_u32 s47, s47, 0
	s_mov_b32 m0, s71
	s_nop 0
	global_load_lds_dwordx4 v136, s[46:47]
	s_waitcnt vmcnt(8)
	s_waitcnt lgkmcnt(0)
	s_barrier
	s_setprio 1
	s_waitcnt lgkmcnt(7)
	s_waitcnt lgkmcnt(0)
	v_mfma_f32_16x16x32_bf16 v[92:95], v[128:131], v[168:171], v[92:95]
	v_mfma_f32_16x16x32_bf16 v[92:95], v[132:135], v[172:175], v[92:95]
	v_mfma_f32_16x16x32_bf16 v[60:63], v[128:131], v[176:179], v[60:63]
	v_mfma_f32_16x16x32_bf16 v[60:63], v[132:135], v[180:183], v[60:63]
	v_mfma_f32_16x16x32_bf16 v[28:31], v[128:131], v[184:187], v[28:31]
	v_mfma_f32_16x16x32_bf16 v[28:31], v[132:135], v[188:191], v[28:31]
	v_mfma_f32_16x16x32_bf16 v[12:15], v[128:131], v[192:195], v[12:15]
	v_mfma_f32_16x16x32_bf16 v[12:15], v[132:135], v[196:199], v[12:15]
	v_mfma_f32_16x16x32_bf16 v[8:11], v[144:147], v[192:195], v[8:11]
	v_mfma_f32_16x16x32_bf16 v[8:11], v[148:151], v[196:199], v[8:11]
	v_mfma_f32_16x16x32_bf16 v[24:27], v[144:147], v[184:187], v[24:27]
	v_mfma_f32_16x16x32_bf16 v[24:27], v[148:151], v[188:191], v[24:27]
	v_mfma_f32_16x16x32_bf16 v[48:51], v[144:147], v[176:179], v[48:51]
	v_mfma_f32_16x16x32_bf16 v[48:51], v[148:151], v[180:183], v[48:51]
	v_mfma_f32_16x16x32_bf16 v[80:83], v[144:147], v[168:171], v[80:83]
	v_mfma_f32_16x16x32_bf16 v[80:83], v[148:151], v[172:175], v[80:83]
	s_setprio 0
	s_setprio 1
	s_waitcnt lgkmcnt(0)
	v_mfma_f32_16x16x32_bf16 v[76:79], v[152:155], v[168:171], v[76:79]
	v_mfma_f32_16x16x32_bf16 v[76:79], v[156:159], v[172:175], v[76:79]
	v_mfma_f32_16x16x32_bf16 v[44:47], v[152:155], v[176:179], v[44:47]
	v_mfma_f32_16x16x32_bf16 v[44:47], v[156:159], v[180:183], v[44:47]
	v_mfma_f32_16x16x32_bf16 v[20:23], v[152:155], v[184:187], v[20:23]
	v_mfma_f32_16x16x32_bf16 v[20:23], v[156:159], v[188:191], v[20:23]
	v_mfma_f32_16x16x32_bf16 v[4:7], v[152:155], v[192:195], v[4:7]
	v_mfma_f32_16x16x32_bf16 v[4:7], v[156:159], v[196:199], v[4:7]
	v_mfma_f32_16x16x32_bf16 v[0:3], v[160:163], v[192:195], v[0:3]
	v_mfma_f32_16x16x32_bf16 v[0:3], v[164:167], v[196:199], v[0:3]
	v_mfma_f32_16x16x32_bf16 v[16:19], v[160:163], v[184:187], v[16:19]
	v_mfma_f32_16x16x32_bf16 v[16:19], v[164:167], v[188:191], v[16:19]
	v_mfma_f32_16x16x32_bf16 v[32:35], v[160:163], v[176:179], v[32:35]
	v_mfma_f32_16x16x32_bf16 v[32:35], v[164:167], v[180:183], v[32:35]
	v_mfma_f32_16x16x32_bf16 v[64:67], v[160:163], v[168:171], v[64:67]
	s_barrier
	v_mfma_f32_16x16x32_bf16 v[64:67], v[164:167], v[172:175], v[64:67]
	s_setprio 0
	s_nop 7
	s_add_i32 s83, s83, 2
	s_add_u32 s81, s81, 0x10000
	s_addc_u32 s82, s82, 0
	s_cmp_gt_u32 s83, 61
	s_mov_b64 s[52:53], s[2:3]
	s_cbranch_scc0 .LBB0_1539
	s_and_b64 vcc, exec, s[8:9]
	s_cbranch_vccz .LBB0_1542
	s_barrier

.LBB0_1675:
	ds_read_b128 v[48:51], v214
	ds_read_b128 v[64:67], v214 offset:1024
	ds_read_b128 v[80:83], v214 offset:2048
	ds_read_b128 v[92:95], v214 offset:3072
	ds_read_b128 v[104:107], v215
	ds_read_b128 v[116:119], v215 offset:1024
	ds_read_b128 v[140:143], v215 offset:2048
	ds_read_b128 v[144:147], v215 offset:3072
	s_cmp_eq_u32 s93, 4
	s_cselect_b32 s2, s89, s54
	s_cselect_b32 s3, s43, s55
	s_cselect_b32 s60, s90, s91
	s_cselect_b32 s61, s41, s92
	s_add_u32 s58, s2, 0x8000
	s_addc_u32 s59, s3, 0
	ds_read_b128 v[156:159], v216
	ds_read_b128 v[168:171], v216 offset:1024
	ds_read_b128 v[172:175], v216 offset:2048
	ds_read_b128 v[176:179], v216 offset:3072
	ds_read_b128 v[180:183], v216 offset:4096
	ds_read_b128 v[184:187], v216 offset:5120
	ds_read_b128 v[188:191], v216 offset:6144
	ds_read_b128 v[194:197], v216 offset:7168
	s_add_u32 s52, s54, 0xffffc000
	s_addc_u32 s53, s55, -1
	s_mov_b32 m0, s77
	s_nop 0
	global_load_lds_dwordx4 v212, s[52:53]
	s_add_u32 s52, s54, 0xffffe000
	s_addc_u32 s53, s55, -1
	s_mov_b32 m0, s81
	s_nop 0
	global_load_lds_dwordx4 v212, s[52:53]
	s_waitcnt vmcnt(8)
	s_waitcnt lgkmcnt(0)
	s_add_u32 s52, s60, 0x8000
	s_addc_u32 s53, s61, 0
	s_barrier
	s_setprio 1
	s_waitcnt lgkmcnt(7)
	v_mfma_f32_16x16x32_bf16 v[164:167], v[48:51], v[156:159], v[164:167]
	v_mfma_f32_16x16x32_bf16 v[160:163], v[80:83], v[156:159], v[160:163]
	s_waitcnt lgkmcnt(5)
	v_mfma_f32_16x16x32_bf16 v[136:139], v[48:51], v[172:175], v[136:139]
	v_mfma_f32_16x16x32_bf16 v[130:133], v[80:83], v[172:175], v[132:135]
	s_waitcnt lgkmcnt(3)
	v_mfma_f32_16x16x32_bf16 v[112:115], v[48:51], v[180:183], v[112:115]
	v_mfma_f32_16x16x32_bf16 v[108:111], v[80:83], v[180:183], v[108:111]
	s_waitcnt lgkmcnt(1)
	v_mfma_f32_16x16x32_bf16 v[88:91], v[48:51], v[188:191], v[88:91]
	v_mfma_f32_16x16x32_bf16 v[84:87], v[80:83], v[188:191], v[84:87]
	v_mfma_f32_16x16x32_bf16 v[164:167], v[64:67], v[168:171], v[164:167]
	v_mfma_f32_16x16x32_bf16 v[160:163], v[92:95], v[168:171], v[160:163]
	v_mfma_f32_16x16x32_bf16 v[136:139], v[64:67], v[176:179], v[136:139]
	v_mfma_f32_16x16x32_bf16 v[130:133], v[92:95], v[176:179], v[130:133]
	v_mfma_f32_16x16x32_bf16 v[112:115], v[64:67], v[184:187], v[112:115]
	v_mfma_f32_16x16x32_bf16 v[108:111], v[92:95], v[184:187], v[108:111]
	s_waitcnt lgkmcnt(0)
	v_mfma_f32_16x16x32_bf16 v[88:91], v[64:67], v[194:197], v[88:91]
	v_mfma_f32_16x16x32_bf16 v[84:87], v[92:95], v[194:197], v[84:87]
	s_setprio 0
	s_setprio 1
	s_waitcnt lgkmcnt(0)
	v_mfma_f32_16x16x32_bf16 v[152:155], v[104:107], v[156:159], v[152:155]
	v_mfma_f32_16x16x32_bf16 v[152:155], v[116:119], v[168:171], v[152:155]
	v_mfma_f32_16x16x32_bf16 v[124:127], v[104:107], v[172:175], v[124:127]
	v_mfma_f32_16x16x32_bf16 v[124:127], v[116:119], v[176:179], v[124:127]
	v_mfma_f32_16x16x32_bf16 v[100:103], v[104:107], v[180:183], v[100:103]
	v_mfma_f32_16x16x32_bf16 v[100:103], v[116:119], v[184:187], v[100:103]
	v_mfma_f32_16x16x32_bf16 v[76:79], v[104:107], v[188:191], v[76:79]
	v_mfma_f32_16x16x32_bf16 v[76:79], v[116:119], v[194:197], v[76:79]
	v_mfma_f32_16x16x32_bf16 v[72:75], v[140:143], v[188:191], v[72:75]
	v_mfma_f32_16x16x32_bf16 v[72:75], v[144:147], v[194:197], v[72:75]
	v_mfma_f32_16x16x32_bf16 v[96:99], v[140:143], v[180:183], v[96:99]
	v_mfma_f32_16x16x32_bf16 v[96:99], v[144:147], v[184:187], v[96:99]
	v_mfma_f32_16x16x32_bf16 v[120:123], v[140:143], v[172:175], v[120:123]
	v_mfma_f32_16x16x32_bf16 v[120:123], v[144:147], v[176:179], v[120:123]
	v_mfma_f32_16x16x32_bf16 v[148:151], v[140:143], v[156:159], v[148:151]
	s_barrier
	v_mfma_f32_16x16x32_bf16 v[148:151], v[144:147], v[168:171], v[148:151]
	s_setprio 0
	s_add_u32 s96, s60, 0x2000
	ds_read_b128 v[156:159], v216 offset:16384
	ds_read_b128 v[168:171], v216 offset:17408
	ds_read_b128 v[172:175], v216 offset:18432
	ds_read_b128 v[176:179], v216 offset:19456
	ds_read_b128 v[180:183], v216 offset:20480
	ds_read_b128 v[184:187], v216 offset:21504
	ds_read_b128 v[188:191], v216 offset:22528
	ds_read_b128 v[194:197], v216 offset:23552
	s_mov_b32 m0, s49
	s_nop 0
	global_load_lds_dwordx4 v212, s[60:61]
	s_addc_u32 s97, s61, 0
	s_mov_b32 m0, s57
	s_nop 0
	global_load_lds_dwordx4 v212, s[96:97]
	s_add_u32 s96, s60, 0x4000
	s_addc_u32 s97, s61, 0
	s_mov_b32 m0, s63
	s_nop 0
	global_load_lds_dwordx4 v212, s[96:97]
	s_add_u32 s96, s60, 0x6000
	s_addc_u32 s97, s61, 0
	s_mov_b32 m0, s64
	s_nop 0
	global_load_lds_dwordx4 v212, s[96:97]
	s_add_u32 s96, s2, 0x2000
	s_mov_b32 m0, s62
	s_nop 0
	global_load_lds_dwordx4 v212, s[2:3]
	s_addc_u32 s97, s3, 0
	s_mov_b32 m0, s65
	s_nop 0
	global_load_lds_dwordx4 v212, s[96:97]
	s_waitcnt vmcnt(8)
	s_waitcnt lgkmcnt(0)
	s_barrier
	s_setprio 1
	s_waitcnt lgkmcnt(7)
	s_waitcnt lgkmcnt(0)
	v_mfma_f32_16x16x32_bf16 v[68:71], v[48:51], v[156:159], v[68:71]
	v_mfma_f32_16x16x32_bf16 v[68:71], v[64:67], v[168:171], v[68:71]
	v_mfma_f32_16x16x32_bf16 v[44:47], v[48:51], v[172:175], v[44:47]
	v_mfma_f32_16x16x32_bf16 v[44:47], v[64:67], v[176:179], v[44:47]
	v_mfma_f32_16x16x32_bf16 v[28:31], v[48:51], v[180:183], v[28:31]
	v_mfma_f32_16x16x32_bf16 v[28:31], v[64:67], v[184:187], v[28:31]
	v_mfma_f32_16x16x32_bf16 v[12:15], v[48:51], v[188:191], v[12:15]
	v_mfma_f32_16x16x32_bf16 v[12:15], v[64:67], v[194:197], v[12:15]
	v_mfma_f32_16x16x32_bf16 v[8:11], v[80:83], v[188:191], v[8:11]
	v_mfma_f32_16x16x32_bf16 v[8:11], v[92:95], v[194:197], v[8:11]
	v_mfma_f32_16x16x32_bf16 v[24:27], v[80:83], v[180:183], v[24:27]
	v_mfma_f32_16x16x32_bf16 v[24:27], v[92:95], v[184:187], v[24:27]
	v_mfma_f32_16x16x32_bf16 v[40:43], v[80:83], v[172:175], v[40:43]
	v_mfma_f32_16x16x32_bf16 v[40:43], v[92:95], v[176:179], v[40:43]
	v_mfma_f32_16x16x32_bf16 v[60:63], v[80:83], v[156:159], v[60:63]
	v_mfma_f32_16x16x32_bf16 v[60:63], v[92:95], v[168:171], v[60:63]
	s_setprio 0
	s_setprio 1
	v_mfma_f32_16x16x32_bf16 v[52:55], v[140:143], v[156:159], v[52:55]
	v_mfma_f32_16x16x32_bf16 v[36:39], v[104:107], v[172:175], v[36:39]
	v_mfma_f32_16x16x32_bf16 v[32:35], v[140:143], v[172:175], v[32:35]
	v_mfma_f32_16x16x32_bf16 v[20:23], v[104:107], v[180:183], v[20:23]
	v_mfma_f32_16x16x32_bf16 v[16:19], v[140:143], v[180:183], v[16:19]
	v_mfma_f32_16x16x32_bf16 v[4:7], v[104:107], v[188:191], v[4:7]
	v_mfma_f32_16x16x32_bf16 v[0:3], v[140:143], v[188:191], v[0:3]
	v_mfma_f32_16x16x32_bf16 v[48:51], v[104:107], v[156:159], v[56:59]
	v_mfma_f32_16x16x32_bf16 v[52:55], v[144:147], v[168:171], v[52:55]
	v_mfma_f32_16x16x32_bf16 v[36:39], v[116:119], v[176:179], v[36:39]
	v_mfma_f32_16x16x32_bf16 v[32:35], v[144:147], v[176:179], v[32:35]
	v_mfma_f32_16x16x32_bf16 v[20:23], v[116:119], v[184:187], v[20:23]
	v_mfma_f32_16x16x32_bf16 v[16:19], v[144:147], v[184:187], v[16:19]
	v_mfma_f32_16x16x32_bf16 v[4:7], v[116:119], v[194:197], v[4:7]
	v_mfma_f32_16x16x32_bf16 v[0:3], v[144:147], v[194:197], v[0:3]
	v_mfma_f32_16x16x32_bf16 v[48:51], v[116:119], v[168:171], v[48:51]
	s_setprio 0
	s_barrier
	ds_read_b128 v[56:59], v128
	ds_read_b128 v[64:67], v128 offset:1024
	ds_read_b128 v[80:83], v128 offset:2048
	ds_read_b128 v[92:95], v128 offset:3072
	ds_read_b128 v[104:107], v129
	ds_read_b128 v[116:119], v129 offset:1024
	ds_read_b128 v[140:143], v129 offset:2048
	ds_read_b128 v[144:147], v129 offset:3072
	ds_read_b128 v[156:159], v216 offset:32768
	ds_read_b128 v[168:171], v216 offset:33792
	ds_read_b128 v[172:175], v216 offset:34816
	ds_read_b128 v[176:179], v216 offset:35840
	ds_read_b128 v[180:183], v216 offset:36864
	ds_read_b128 v[184:187], v216 offset:37888
	ds_read_b128 v[188:191], v216 offset:38912
	ds_read_b128 v[194:197], v216 offset:39936
	s_add_u32 s96, s2, 0x4000
	s_addc_u32 s97, s3, 0
	s_mov_b32 m0, s66
	s_nop 0
	global_load_lds_dwordx4 v212, s[96:97]
	s_add_u32 s96, s2, 0x6000
	s_addc_u32 s97, s3, 0
	s_mov_b32 m0, s67
	s_nop 0
	global_load_lds_dwordx4 v212, s[96:97]
	s_waitcnt vmcnt(8)
	s_waitcnt lgkmcnt(0)
	s_barrier
	s_setprio 1
	s_waitcnt lgkmcnt(7)
	v_mfma_f32_16x16x32_bf16 v[164:167], v[56:59], v[156:159], v[164:167]
	v_mfma_f32_16x16x32_bf16 v[160:163], v[80:83], v[156:159], v[160:163]
	s_waitcnt lgkmcnt(5)
	v_mfma_f32_16x16x32_bf16 v[134:137], v[56:59], v[172:175], v[136:139]
	v_mfma_f32_16x16x32_bf16 v[130:133], v[80:83], v[172:175], v[130:133]
	s_waitcnt lgkmcnt(3)
	v_mfma_f32_16x16x32_bf16 v[112:115], v[56:59], v[180:183], v[112:115]
	v_mfma_f32_16x16x32_bf16 v[108:111], v[80:83], v[180:183], v[108:111]
	s_waitcnt lgkmcnt(1)
	v_mfma_f32_16x16x32_bf16 v[88:91], v[56:59], v[188:191], v[88:91]
	v_mfma_f32_16x16x32_bf16 v[84:87], v[80:83], v[188:191], v[84:87]
	v_mfma_f32_16x16x32_bf16 v[164:167], v[64:67], v[168:171], v[164:167]
	v_mfma_f32_16x16x32_bf16 v[160:163], v[92:95], v[168:171], v[160:163]
	v_mfma_f32_16x16x32_bf16 v[136:139], v[64:67], v[176:179], v[134:137]
	v_mfma_f32_16x16x32_bf16 v[132:135], v[92:95], v[176:179], v[130:133]
	v_mfma_f32_16x16x32_bf16 v[112:115], v[64:67], v[184:187], v[112:115]
	v_mfma_f32_16x16x32_bf16 v[108:111], v[92:95], v[184:187], v[108:111]
	s_waitcnt lgkmcnt(0)
	v_mfma_f32_16x16x32_bf16 v[88:91], v[64:67], v[194:197], v[88:91]
	v_mfma_f32_16x16x32_bf16 v[84:87], v[92:95], v[194:197], v[84:87]
	s_setprio 0
	s_setprio 1
	s_waitcnt lgkmcnt(0)
	v_mfma_f32_16x16x32_bf16 v[152:155], v[104:107], v[156:159], v[152:155]
	v_mfma_f32_16x16x32_bf16 v[152:155], v[116:119], v[168:171], v[152:155]
	v_mfma_f32_16x16x32_bf16 v[124:127], v[104:107], v[172:175], v[124:127]
	v_mfma_f32_16x16x32_bf16 v[124:127], v[116:119], v[176:179], v[124:127]
	v_mfma_f32_16x16x32_bf16 v[100:103], v[104:107], v[180:183], v[100:103]
	v_mfma_f32_16x16x32_bf16 v[100:103], v[116:119], v[184:187], v[100:103]
	v_mfma_f32_16x16x32_bf16 v[76:79], v[104:107], v[188:191], v[76:79]
	v_mfma_f32_16x16x32_bf16 v[76:79], v[116:119], v[194:197], v[76:79]
	v_mfma_f32_16x16x32_bf16 v[72:75], v[140:143], v[188:191], v[72:75]
	v_mfma_f32_16x16x32_bf16 v[72:75], v[144:147], v[194:197], v[72:75]
	v_mfma_f32_16x16x32_bf16 v[96:99], v[140:143], v[180:183], v[96:99]
	v_mfma_f32_16x16x32_bf16 v[96:99], v[144:147], v[184:187], v[96:99]
	v_mfma_f32_16x16x32_bf16 v[120:123], v[140:143], v[172:175], v[120:123]
	v_mfma_f32_16x16x32_bf16 v[120:123], v[144:147], v[176:179], v[120:123]
	v_mfma_f32_16x16x32_bf16 v[148:151], v[140:143], v[156:159], v[148:151]
	s_barrier
	v_mfma_f32_16x16x32_bf16 v[148:151], v[144:147], v[168:171], v[148:151]
	s_setprio 0
	ds_read_b128 v[156:159], v216 offset:49152
	ds_read_b128 v[168:171], v216 offset:50176
	ds_read_b128 v[172:175], v216 offset:51200
	ds_read_b128 v[176:179], v216 offset:52224
	ds_read_b128 v[180:183], v216 offset:53248
	ds_read_b128 v[184:187], v216 offset:54272
	ds_read_b128 v[188:191], v216 offset:55296
	ds_read_b128 v[194:197], v216 offset:56320
	s_mov_b32 m0, s71
	s_nop 0
	global_load_lds_dwordx4 v212, s[52:53]
	s_add_u32 s52, s60, 0xa000
	s_addc_u32 s53, s61, 0
	s_mov_b32 m0, s72
	s_nop 0
	global_load_lds_dwordx4 v212, s[52:53]
	s_add_u32 s52, s60, 0xc000
	s_addc_u32 s53, s61, 0
	s_mov_b32 m0, s75
	s_nop 0
	global_load_lds_dwordx4 v212, s[52:53]
	s_add_u32 s52, s60, 0xe000
	s_addc_u32 s53, s61, 0
	s_mov_b32 m0, s76
	s_nop 0
	global_load_lds_dwordx4 v212, s[52:53]
	s_add_u32 s2, s2, 0xa000
	s_mov_b32 m0, s73
	s_nop 0
	global_load_lds_dwordx4 v212, s[58:59]
	s_addc_u32 s3, s3, 0
	s_mov_b32 m0, s74
	s_nop 0
	global_load_lds_dwordx4 v212, s[2:3]
	s_waitcnt vmcnt(8)
	s_waitcnt lgkmcnt(0)
	s_barrier
	s_setprio 1
	s_waitcnt lgkmcnt(7)
	s_waitcnt lgkmcnt(0)
	v_mfma_f32_16x16x32_bf16 v[68:71], v[56:59], v[156:159], v[68:71]
	v_mfma_f32_16x16x32_bf16 v[68:71], v[64:67], v[168:171], v[68:71]
	v_mfma_f32_16x16x32_bf16 v[44:47], v[56:59], v[172:175], v[44:47]
	v_mfma_f32_16x16x32_bf16 v[44:47], v[64:67], v[176:179], v[44:47]
	v_mfma_f32_16x16x32_bf16 v[28:31], v[56:59], v[180:183], v[28:31]
	v_mfma_f32_16x16x32_bf16 v[28:31], v[64:67], v[184:187], v[28:31]
	v_mfma_f32_16x16x32_bf16 v[12:15], v[56:59], v[188:191], v[12:15]
	v_mfma_f32_16x16x32_bf16 v[12:15], v[64:67], v[194:197], v[12:15]
	v_mfma_f32_16x16x32_bf16 v[8:11], v[80:83], v[188:191], v[8:11]
	v_mfma_f32_16x16x32_bf16 v[8:11], v[92:95], v[194:197], v[8:11]
	v_mfma_f32_16x16x32_bf16 v[24:27], v[80:83], v[180:183], v[24:27]
	v_mfma_f32_16x16x32_bf16 v[24:27], v[92:95], v[184:187], v[24:27]
	v_mfma_f32_16x16x32_bf16 v[40:43], v[80:83], v[172:175], v[40:43]
	v_mfma_f32_16x16x32_bf16 v[40:43], v[92:95], v[176:179], v[40:43]
	v_mfma_f32_16x16x32_bf16 v[60:63], v[80:83], v[156:159], v[60:63]
	v_mfma_f32_16x16x32_bf16 v[60:63], v[92:95], v[168:171], v[60:63]
	s_setprio 0
	s_setprio 1
	v_mfma_f32_16x16x32_bf16 v[48:51], v[104:107], v[156:159], v[48:51]
	v_mfma_f32_16x16x32_bf16 v[56:59], v[116:119], v[168:171], v[48:51]
	v_mfma_f32_16x16x32_bf16 v[48:51], v[140:143], v[156:159], v[52:55]
	v_mfma_f32_16x16x32_bf16 v[36:39], v[104:107], v[172:175], v[36:39]
	v_mfma_f32_16x16x32_bf16 v[32:35], v[140:143], v[172:175], v[32:35]
	v_mfma_f32_16x16x32_bf16 v[20:23], v[104:107], v[180:183], v[20:23]
	v_mfma_f32_16x16x32_bf16 v[16:19], v[140:143], v[180:183], v[16:19]
	v_mfma_f32_16x16x32_bf16 v[4:7], v[104:107], v[188:191], v[4:7]
	v_mfma_f32_16x16x32_bf16 v[0:3], v[140:143], v[188:191], v[0:3]
	v_mfma_f32_16x16x32_bf16 v[52:55], v[144:147], v[168:171], v[48:51]
	v_mfma_f32_16x16x32_bf16 v[36:39], v[116:119], v[176:179], v[36:39]
	v_mfma_f32_16x16x32_bf16 v[32:35], v[144:147], v[176:179], v[32:35]
	v_mfma_f32_16x16x32_bf16 v[20:23], v[116:119], v[184:187], v[20:23]
	v_mfma_f32_16x16x32_bf16 v[16:19], v[144:147], v[184:187], v[16:19]
	v_mfma_f32_16x16x32_bf16 v[4:7], v[116:119], v[194:197], v[4:7]
	v_mfma_f32_16x16x32_bf16 v[0:3], v[144:147], v[194:197], v[0:3]
	s_setprio 0
	s_barrier
	s_add_i32 s93, s93, 2
	s_add_u32 s54, s54, 0x10000
	s_addc_u32 s55, s55, 0
	s_add_u32 s91, s91, 0x10000
	s_addc_u32 s92, s92, 0
	s_cmp_gt_u32 s93, 5
	s_cbranch_scc0 .LBB0_1675
	s_and_b64 vcc, exec, s[14:15]
	s_cbranch_vccz .LBB0_1678
	s_barrier

.LBB0_1953:
	ds_read_b128 v[134:137], v128
	ds_read_b128 v[138:141], v128 offset:1024
	ds_read_b128 v[142:145], v128 offset:2048
	ds_read_b128 v[146:149], v128 offset:3072
	ds_read_b128 v[150:153], v129
	ds_read_b128 v[154:157], v129 offset:1024
	ds_read_b128 v[158:161], v129 offset:2048
	ds_read_b128 v[162:165], v129 offset:3072
	s_add_u32 s2, s28, 0x10000
	s_addc_u32 s3, s29, 0
	s_cmp_eq_u32 s77, 8
	s_cselect_b32 s38, s26, s2
	s_cselect_b32 s39, s27, s3
	s_cselect_b32 s42, s23, s75
	s_cselect_b32 s43, s25, s76
	s_add_u32 s40, s38, 0x8000
	s_addc_u32 s41, s39, 0
	ds_read_b128 v[166:169], v130
	ds_read_b128 v[170:173], v130 offset:1024
	ds_read_b128 v[174:177], v130 offset:2048
	ds_read_b128 v[178:181], v130 offset:3072
	ds_read_b128 v[182:185], v130 offset:4096
	ds_read_b128 v[192:195], v130 offset:5120
	ds_read_b128 v[196:199], v130 offset:6144
	ds_read_b128 v[200:203], v130 offset:7168
	s_add_u32 s78, s28, 0xc000
	s_addc_u32 s79, s29, 0
	s_mov_b32 m0, s63
	s_nop 0
	global_load_lds_dwordx4 v210, s[78:79]
	s_add_u32 s28, s28, 0xe000
	s_addc_u32 s29, s29, 0
	s_mov_b32 m0, s66
	s_nop 0
	global_load_lds_dwordx4 v210, s[28:29]
	s_waitcnt vmcnt(8)
	s_waitcnt lgkmcnt(0)
	s_barrier
	s_setprio 1
	s_waitcnt lgkmcnt(7)
	s_waitcnt lgkmcnt(0)
	v_mfma_f32_16x16x32_bf16 v[124:127], v[134:137], v[166:169], v[124:127]
	v_mfma_f32_16x16x32_bf16 v[124:127], v[138:141], v[170:173], v[124:127]
	v_mfma_f32_16x16x32_bf16 v[108:111], v[134:137], v[174:177], v[108:111]
	v_mfma_f32_16x16x32_bf16 v[108:111], v[138:141], v[178:181], v[108:111]
	v_mfma_f32_16x16x32_bf16 v[92:95], v[134:137], v[182:185], v[92:95]
	v_mfma_f32_16x16x32_bf16 v[92:95], v[138:141], v[192:195], v[92:95]
	v_mfma_f32_16x16x32_bf16 v[76:79], v[134:137], v[196:199], v[76:79]
	v_mfma_f32_16x16x32_bf16 v[76:79], v[138:141], v[200:203], v[76:79]
	v_mfma_f32_16x16x32_bf16 v[72:75], v[142:145], v[196:199], v[72:75]
	v_mfma_f32_16x16x32_bf16 v[72:75], v[146:149], v[200:203], v[72:75]
	v_mfma_f32_16x16x32_bf16 v[88:91], v[142:145], v[182:185], v[88:91]
	v_mfma_f32_16x16x32_bf16 v[88:91], v[146:149], v[192:195], v[88:91]
	v_mfma_f32_16x16x32_bf16 v[104:107], v[142:145], v[174:177], v[104:107]
	v_mfma_f32_16x16x32_bf16 v[104:107], v[146:149], v[178:181], v[104:107]
	v_mfma_f32_16x16x32_bf16 v[120:123], v[142:145], v[166:169], v[120:123]
	v_mfma_f32_16x16x32_bf16 v[120:123], v[146:149], v[170:173], v[120:123]
	s_setprio 0
	s_setprio 1
	s_waitcnt lgkmcnt(0)
	v_mfma_f32_16x16x32_bf16 v[116:119], v[150:153], v[166:169], v[116:119]
	v_mfma_f32_16x16x32_bf16 v[116:119], v[154:157], v[170:173], v[116:119]
	v_mfma_f32_16x16x32_bf16 v[100:103], v[150:153], v[174:177], v[100:103]
	v_mfma_f32_16x16x32_bf16 v[100:103], v[154:157], v[178:181], v[100:103]
	v_mfma_f32_16x16x32_bf16 v[84:87], v[150:153], v[182:185], v[84:87]
	v_mfma_f32_16x16x32_bf16 v[84:87], v[154:157], v[192:195], v[84:87]
	v_mfma_f32_16x16x32_bf16 v[68:71], v[150:153], v[196:199], v[68:71]
	v_mfma_f32_16x16x32_bf16 v[68:71], v[154:157], v[200:203], v[68:71]
	v_mfma_f32_16x16x32_bf16 v[64:67], v[158:161], v[196:199], v[64:67]
	v_mfma_f32_16x16x32_bf16 v[64:67], v[162:165], v[200:203], v[64:67]
	v_mfma_f32_16x16x32_bf16 v[80:83], v[158:161], v[182:185], v[80:83]
	v_mfma_f32_16x16x32_bf16 v[80:83], v[162:165], v[192:195], v[80:83]
	v_mfma_f32_16x16x32_bf16 v[96:99], v[158:161], v[174:177], v[96:99]
	v_mfma_f32_16x16x32_bf16 v[96:99], v[162:165], v[178:181], v[96:99]
	v_mfma_f32_16x16x32_bf16 v[112:115], v[158:161], v[166:169], v[112:115]
	s_barrier
	v_mfma_f32_16x16x32_bf16 v[112:115], v[162:165], v[170:173], v[112:115]
	s_setprio 0
	s_add_u32 s28, s42, 0x2000
	ds_read_b128 v[166:169], v130 offset:16384
	ds_read_b128 v[170:173], v130 offset:17408
	ds_read_b128 v[174:177], v130 offset:18432
	ds_read_b128 v[178:181], v130 offset:19456
	ds_read_b128 v[182:185], v130 offset:20480
	ds_read_b128 v[192:195], v130 offset:21504
	ds_read_b128 v[196:199], v130 offset:22528
	ds_read_b128 v[200:203], v130 offset:23552
	s_mov_b32 m0, s46
	s_nop 0
	global_load_lds_dwordx4 v210, s[42:43]
	s_addc_u32 s29, s43, 0
	s_mov_b32 m0, s47
	s_nop 0
	global_load_lds_dwordx4 v210, s[28:29]
	s_add_u32 s28, s42, 0x4000
	s_addc_u32 s29, s43, 0
	s_mov_b32 m0, s48
	s_nop 0
	global_load_lds_dwordx4 v210, s[28:29]
	s_add_u32 s28, s42, 0x6000
	s_addc_u32 s29, s43, 0
	s_mov_b32 m0, s49
	s_nop 0
	global_load_lds_dwordx4 v210, s[28:29]
	s_add_u32 s28, s38, 0x2000
	s_mov_b32 m0, s45
	s_nop 0
	global_load_lds_dwordx4 v210, s[38:39]
	s_addc_u32 s29, s39, 0
	s_mov_b32 m0, s50
	s_nop 0
	global_load_lds_dwordx4 v210, s[28:29]
	s_waitcnt vmcnt(8)
	s_waitcnt lgkmcnt(0)
	s_barrier
	s_setprio 1
	s_waitcnt lgkmcnt(7)
	s_waitcnt lgkmcnt(0)
	v_mfma_f32_16x16x32_bf16 v[60:63], v[134:137], v[166:169], v[60:63]
	v_mfma_f32_16x16x32_bf16 v[60:63], v[138:141], v[170:173], v[60:63]
	v_mfma_f32_16x16x32_bf16 v[44:47], v[134:137], v[174:177], v[44:47]
	v_mfma_f32_16x16x32_bf16 v[44:47], v[138:141], v[178:181], v[44:47]
	v_mfma_f32_16x16x32_bf16 v[28:31], v[134:137], v[182:185], v[28:31]
	v_mfma_f32_16x16x32_bf16 v[28:31], v[138:141], v[192:195], v[28:31]
	v_mfma_f32_16x16x32_bf16 v[12:15], v[134:137], v[196:199], v[12:15]
	v_mfma_f32_16x16x32_bf16 v[12:15], v[138:141], v[200:203], v[12:15]
	v_mfma_f32_16x16x32_bf16 v[8:11], v[142:145], v[196:199], v[8:11]
	v_mfma_f32_16x16x32_bf16 v[8:11], v[146:149], v[200:203], v[8:11]
	v_mfma_f32_16x16x32_bf16 v[24:27], v[142:145], v[182:185], v[24:27]
	v_mfma_f32_16x16x32_bf16 v[24:27], v[146:149], v[192:195], v[24:27]
	v_mfma_f32_16x16x32_bf16 v[40:43], v[142:145], v[174:177], v[40:43]
	v_mfma_f32_16x16x32_bf16 v[40:43], v[146:149], v[178:181], v[40:43]
	v_mfma_f32_16x16x32_bf16 v[56:59], v[142:145], v[166:169], v[56:59]
	v_mfma_f32_16x16x32_bf16 v[56:59], v[146:149], v[170:173], v[56:59]
	s_setprio 0
	s_setprio 1
	s_waitcnt lgkmcnt(0)
	v_mfma_f32_16x16x32_bf16 v[52:55], v[150:153], v[166:169], v[52:55]
	v_mfma_f32_16x16x32_bf16 v[52:55], v[154:157], v[170:173], v[52:55]
	v_mfma_f32_16x16x32_bf16 v[36:39], v[150:153], v[174:177], v[36:39]
	v_mfma_f32_16x16x32_bf16 v[36:39], v[154:157], v[178:181], v[36:39]
	v_mfma_f32_16x16x32_bf16 v[20:23], v[150:153], v[182:185], v[20:23]
	v_mfma_f32_16x16x32_bf16 v[20:23], v[154:157], v[192:195], v[20:23]
	v_mfma_f32_16x16x32_bf16 v[4:7], v[150:153], v[196:199], v[4:7]
	v_mfma_f32_16x16x32_bf16 v[4:7], v[154:157], v[200:203], v[4:7]
	v_mfma_f32_16x16x32_bf16 v[0:3], v[158:161], v[196:199], v[0:3]
	v_mfma_f32_16x16x32_bf16 v[0:3], v[162:165], v[200:203], v[0:3]
	v_mfma_f32_16x16x32_bf16 v[16:19], v[158:161], v[182:185], v[16:19]
	v_mfma_f32_16x16x32_bf16 v[16:19], v[162:165], v[192:195], v[16:19]
	v_mfma_f32_16x16x32_bf16 v[32:35], v[158:161], v[174:177], v[32:35]
	v_mfma_f32_16x16x32_bf16 v[32:35], v[162:165], v[178:181], v[32:35]
	v_mfma_f32_16x16x32_bf16 v[48:51], v[158:161], v[166:169], v[48:51]
	s_barrier
	v_mfma_f32_16x16x32_bf16 v[48:51], v[162:165], v[170:173], v[48:51]
	s_setprio 0
	ds_read_b128 v[134:137], v131
	ds_read_b128 v[138:141], v131 offset:1024
	ds_read_b128 v[142:145], v131 offset:2048
	ds_read_b128 v[146:149], v131 offset:3072
	ds_read_b128 v[150:153], v132
	ds_read_b128 v[154:157], v132 offset:1024
	ds_read_b128 v[158:161], v132 offset:2048
	ds_read_b128 v[162:165], v132 offset:3072
	ds_read_b128 v[166:169], v130 offset:32768
	ds_read_b128 v[170:173], v130 offset:33792
	ds_read_b128 v[174:177], v130 offset:34816
	ds_read_b128 v[178:181], v130 offset:35840
	ds_read_b128 v[182:185], v130 offset:36864
	ds_read_b128 v[192:195], v130 offset:37888
	ds_read_b128 v[196:199], v130 offset:38912
	ds_read_b128 v[200:203], v130 offset:39936
	s_add_u32 s28, s38, 0x4000
	s_addc_u32 s29, s39, 0
	s_mov_b32 m0, s51
	s_nop 0
	global_load_lds_dwordx4 v210, s[28:29]
	s_add_u32 s28, s38, 0x6000
	s_addc_u32 s29, s39, 0
	s_mov_b32 m0, s52
	s_nop 0
	global_load_lds_dwordx4 v210, s[28:29]
	s_waitcnt vmcnt(8)
	s_waitcnt lgkmcnt(0)
	s_barrier
	s_setprio 1
	s_waitcnt lgkmcnt(7)
	s_waitcnt lgkmcnt(0)
	v_mfma_f32_16x16x32_bf16 v[124:127], v[134:137], v[166:169], v[124:127]
	v_mfma_f32_16x16x32_bf16 v[124:127], v[138:141], v[170:173], v[124:127]
	v_mfma_f32_16x16x32_bf16 v[108:111], v[134:137], v[174:177], v[108:111]
	v_mfma_f32_16x16x32_bf16 v[108:111], v[138:141], v[178:181], v[108:111]
	v_mfma_f32_16x16x32_bf16 v[92:95], v[134:137], v[182:185], v[92:95]
	v_mfma_f32_16x16x32_bf16 v[92:95], v[138:141], v[192:195], v[92:95]
	v_mfma_f32_16x16x32_bf16 v[76:79], v[134:137], v[196:199], v[76:79]
	v_mfma_f32_16x16x32_bf16 v[76:79], v[138:141], v[200:203], v[76:79]
	v_mfma_f32_16x16x32_bf16 v[72:75], v[142:145], v[196:199], v[72:75]
	v_mfma_f32_16x16x32_bf16 v[72:75], v[146:149], v[200:203], v[72:75]
	v_mfma_f32_16x16x32_bf16 v[88:91], v[142:145], v[182:185], v[88:91]
	v_mfma_f32_16x16x32_bf16 v[88:91], v[146:149], v[192:195], v[88:91]
	v_mfma_f32_16x16x32_bf16 v[104:107], v[142:145], v[174:177], v[104:107]
	v_mfma_f32_16x16x32_bf16 v[104:107], v[146:149], v[178:181], v[104:107]
	v_mfma_f32_16x16x32_bf16 v[120:123], v[142:145], v[166:169], v[120:123]
	v_mfma_f32_16x16x32_bf16 v[120:123], v[146:149], v[170:173], v[120:123]
	s_setprio 0
	s_setprio 1
	s_waitcnt lgkmcnt(0)
	v_mfma_f32_16x16x32_bf16 v[116:119], v[150:153], v[166:169], v[116:119]
	v_mfma_f32_16x16x32_bf16 v[116:119], v[154:157], v[170:173], v[116:119]
	v_mfma_f32_16x16x32_bf16 v[100:103], v[150:153], v[174:177], v[100:103]
	v_mfma_f32_16x16x32_bf16 v[100:103], v[154:157], v[178:181], v[100:103]
	v_mfma_f32_16x16x32_bf16 v[84:87], v[150:153], v[182:185], v[84:87]
	v_mfma_f32_16x16x32_bf16 v[84:87], v[154:157], v[192:195], v[84:87]
	v_mfma_f32_16x16x32_bf16 v[68:71], v[150:153], v[196:199], v[68:71]
	v_mfma_f32_16x16x32_bf16 v[68:71], v[154:157], v[200:203], v[68:71]
	v_mfma_f32_16x16x32_bf16 v[64:67], v[158:161], v[196:199], v[64:67]
	v_mfma_f32_16x16x32_bf16 v[64:67], v[162:165], v[200:203], v[64:67]
	v_mfma_f32_16x16x32_bf16 v[80:83], v[158:161], v[182:185], v[80:83]
	v_mfma_f32_16x16x32_bf16 v[80:83], v[162:165], v[192:195], v[80:83]
	v_mfma_f32_16x16x32_bf16 v[96:99], v[158:161], v[174:177], v[96:99]
	v_mfma_f32_16x16x32_bf16 v[96:99], v[162:165], v[178:181], v[96:99]
	v_mfma_f32_16x16x32_bf16 v[112:115], v[158:161], v[166:169], v[112:115]
	s_barrier
	v_mfma_f32_16x16x32_bf16 v[112:115], v[162:165], v[170:173], v[112:115]
	s_setprio 0
	s_add_u32 s28, s42, 0x8000
	s_addc_u32 s29, s43, 0
	ds_read_b128 v[166:169], v130 offset:49152
	ds_read_b128 v[170:173], v130 offset:50176
	ds_read_b128 v[174:177], v130 offset:51200
	ds_read_b128 v[178:181], v130 offset:52224
	ds_read_b128 v[182:185], v130 offset:53248
	ds_read_b128 v[192:195], v130 offset:54272
	ds_read_b128 v[196:199], v130 offset:55296
	ds_read_b128 v[200:203], v130 offset:56320
	s_mov_b32 m0, s53
	s_nop 0
	global_load_lds_dwordx4 v210, s[28:29]
	s_add_u32 s28, s42, 0xa000
	s_addc_u32 s29, s43, 0
	s_mov_b32 m0, s54
	s_nop 0
	global_load_lds_dwordx4 v210, s[28:29]
	s_add_u32 s28, s42, 0xc000
	s_addc_u32 s29, s43, 0
	s_mov_b32 m0, s57
	s_nop 0
	global_load_lds_dwordx4 v210, s[28:29]
	s_add_u32 s28, s42, 0xe000
	s_addc_u32 s29, s43, 0
	s_mov_b32 m0, s58
	s_nop 0
	global_load_lds_dwordx4 v210, s[28:29]
	s_add_u32 s28, s38, 0xa000
	s_mov_b32 m0, s55
	s_nop 0
	global_load_lds_dwordx4 v210, s[40:41]
	s_addc_u32 s29, s39, 0
	s_mov_b32 m0, s56
	s_nop 0
	global_load_lds_dwordx4 v210, s[28:29]
	s_waitcnt vmcnt(8)
	s_waitcnt lgkmcnt(0)
	s_barrier
	s_setprio 1
	s_waitcnt lgkmcnt(7)
	s_waitcnt lgkmcnt(0)
	v_mfma_f32_16x16x32_bf16 v[60:63], v[134:137], v[166:169], v[60:63]
	v_mfma_f32_16x16x32_bf16 v[60:63], v[138:141], v[170:173], v[60:63]
	v_mfma_f32_16x16x32_bf16 v[44:47], v[134:137], v[174:177], v[44:47]
	v_mfma_f32_16x16x32_bf16 v[44:47], v[138:141], v[178:181], v[44:47]
	v_mfma_f32_16x16x32_bf16 v[28:31], v[134:137], v[182:185], v[28:31]
	v_mfma_f32_16x16x32_bf16 v[28:31], v[138:141], v[192:195], v[28:31]
	v_mfma_f32_16x16x32_bf16 v[12:15], v[134:137], v[196:199], v[12:15]
	v_mfma_f32_16x16x32_bf16 v[12:15], v[138:141], v[200:203], v[12:15]
	v_mfma_f32_16x16x32_bf16 v[8:11], v[142:145], v[196:199], v[8:11]
	v_mfma_f32_16x16x32_bf16 v[8:11], v[146:149], v[200:203], v[8:11]
	v_mfma_f32_16x16x32_bf16 v[24:27], v[142:145], v[182:185], v[24:27]
	v_mfma_f32_16x16x32_bf16 v[24:27], v[146:149], v[192:195], v[24:27]
	v_mfma_f32_16x16x32_bf16 v[40:43], v[142:145], v[174:177], v[40:43]
	v_mfma_f32_16x16x32_bf16 v[40:43], v[146:149], v[178:181], v[40:43]
	v_mfma_f32_16x16x32_bf16 v[56:59], v[142:145], v[166:169], v[56:59]
	v_mfma_f32_16x16x32_bf16 v[56:59], v[146:149], v[170:173], v[56:59]
	s_setprio 0
	s_setprio 1
	s_waitcnt lgkmcnt(0)
	v_mfma_f32_16x16x32_bf16 v[52:55], v[150:153], v[166:169], v[52:55]
	v_mfma_f32_16x16x32_bf16 v[52:55], v[154:157], v[170:173], v[52:55]
	v_mfma_f32_16x16x32_bf16 v[36:39], v[150:153], v[174:177], v[36:39]
	v_mfma_f32_16x16x32_bf16 v[36:39], v[154:157], v[178:181], v[36:39]
	v_mfma_f32_16x16x32_bf16 v[20:23], v[150:153], v[182:185], v[20:23]
	v_mfma_f32_16x16x32_bf16 v[20:23], v[154:157], v[192:195], v[20:23]
	v_mfma_f32_16x16x32_bf16 v[4:7], v[150:153], v[196:199], v[4:7]
	v_mfma_f32_16x16x32_bf16 v[4:7], v[154:157], v[200:203], v[4:7]
	v_mfma_f32_16x16x32_bf16 v[0:3], v[158:161], v[196:199], v[0:3]
	v_mfma_f32_16x16x32_bf16 v[0:3], v[162:165], v[200:203], v[0:3]
	v_mfma_f32_16x16x32_bf16 v[16:19], v[158:161], v[182:185], v[16:19]
	v_mfma_f32_16x16x32_bf16 v[16:19], v[162:165], v[192:195], v[16:19]
	v_mfma_f32_16x16x32_bf16 v[32:35], v[158:161], v[174:177], v[32:35]
	v_mfma_f32_16x16x32_bf16 v[32:35], v[162:165], v[178:181], v[32:35]
	v_mfma_f32_16x16x32_bf16 v[48:51], v[158:161], v[166:169], v[48:51]
	s_barrier
	v_mfma_f32_16x16x32_bf16 v[48:51], v[162:165], v[170:173], v[48:51]
	s_setprio 0
	s_nop 7
	s_add_i32 s77, s77, 2
	s_add_u32 s75, s75, 0x10000
	s_addc_u32 s76, s76, 0
	s_cmp_gt_u32 s77, 9
	s_mov_b64 s[28:29], s[2:3]
	s_cbranch_scc0 .LBB0_1953
	v_mbcnt_lo_u32_b32 v128, -1, 0
	v_mbcnt_hi_u32_b32 v128, -1, v128
	s_add_u32 s19, s69, s19
	v_lshlrev_b32_e32 v128, 4, v128
	v_add_u32_e32 v129, s60, v128
	v_add_u32_e32 v128, s62, v128
	s_addc_u32 s17, s70, s17
	s_mov_b32 s23, -2
	v_add_u32_e32 v128, 0, v128
	v_add_u32_e32 v129, 0, v129
